# DF unit epilogue: 5-step ds_bpermute row reductions replaced by DPP moves + v_permlane16_swap (bit-identical); plus widened SB epilogue stores
# speedup vs baseline: 1.0034x; 1.0034x over previous
; #define LAS __attribute__((address_space(3)))
; __device__ __forceinline__ bf16_t f2bf(float f) { unsigned u = __float_as_uint(f); u += 0x7FFFu + ((u >> 16) & 1u); return (bf16_t)(u >> 16); }
; #define ATT_SYNC() do { asm volatile("s_waitcnt vmcnt(0) lgkmcnt(0)" ::: "memory"); __builtin_amdgcn_s_barrier(); asm volatile("" ::: "memory"); } while (0)
; __device__ __forceinline__ void df_unit(LAS unsigned char* lds, const bf16_t* qkv, bf16_t* attout, const float* subg, int b_, int h_, int qb_, int wid, int) {
;     ...
;     ATT_SYNC();
;     if (jsel == 0) {
;         bf16_t* op = attout + (size_t)(b * SEQ + q0 + 4 * hi) * DM + 1024 + h * 256 + r32; const LAS float* xr = xb + (4 * hi) * 256 + r32;
; #pragma unroll
;         for (int r = 0; r < 16; ++r) { const int rowc = (r & 3) + 8 * (r >> 2); float ss = 0.f;
; #pragma unroll
;             for (int d = 0; d < 8; ++d) { o[d][r] -= xr[rowc * 256 + d * 32]; ss += o[d][r] * o[d][r]; }
;             ss += __shfl_xor(ss, 1); ss += __shfl_xor(ss, 2); ss += __shfl_xor(ss, 4); ss += __shfl_xor(ss, 8); ss += __shfl_xor(ss, 16);
;             const float rstd = (1.0f - LAMBDA_INIT) / sqrtf(ss * (1.0f / 256.0f) + SUBLN_EPS);
; #pragma unroll
;             for (int d = 0; d < 8; ++d) op[d * 32] = f2bf(o[d][r] * rstd * subg[d * 32 + r32]);
;             op += ((r & 3) == 3 ? 5 : 1) * DM; asm volatile("" : "+v"(op) :: "memory"); } }
.LBB0_299:
	s_waitcnt vmcnt(0) lgkmcnt(0)
	s_barrier
	s_andn2_b64 vcc, exec, s[10:11]
	s_cbranch_vccnz .LBB0_260
	v_lshlrev_b32_e32 v3, 12, v193
	v_lshlrev_b32_e32 v13, 2, v178
	v_add3_u32 v13, s53, v3, v13
	ds_read2_b32 v[32:33], v13 offset1:32
	v_ashrrev_i32_e32 v179, 31, v178
	ds_read2_b32 v[46:47], v13 offset0:64 offset1:96
	s_lshl_b32 s0, s33, 12
	s_add_i32 s42, s42, s0
	s_waitcnt lgkmcnt(1)
	v_sub_f32_e32 v17, v177, v32
	v_sub_f32_e32 v31, v180, v33
	ds_read2_b32 v[32:33], v13 offset0:128 offset1:160
	v_mul_f32_e32 v48, v31, v31
	s_waitcnt lgkmcnt(1)
	v_sub_f32_e32 v49, v176, v46
	v_sub_f32_e32 v60, v175, v47
	ds_read2_b32 v[46:47], v13 offset0:192 offset1:224
	s_waitcnt lgkmcnt(1)
	v_sub_f32_e32 v61, v2, v32
	v_lshl_add_u64 v[2:3], v[178:179], 2, s[58:59]
	global_load_dword v62, v[2:3], off
	global_load_dword v64, v[2:3], off offset:128
	global_load_dword v65, v[2:3], off offset:256
	global_load_dword v75, v[2:3], off offset:384
	global_load_dword v76, v[2:3], off offset:640
	global_load_dword v77, v[2:3], off offset:768
	global_load_dword v78, v[2:3], off offset:896
	v_fmac_f32_e32 v48, v17, v17
	v_fmac_f32_e32 v48, v49, v49
	v_fmac_f32_e32 v48, v60, v60
	v_fmac_f32_e32 v48, v61, v61
	v_sub_f32_e32 v63, v174, v33
	v_fmac_f32_e32 v48, v63, v63
	s_waitcnt lgkmcnt(0)
	v_sub_f32_e32 v46, v173, v46
	v_fmac_f32_e32 v48, v46, v46
	v_sub_f32_e32 v47, v172, v47
	v_fmac_f32_e32 v48, v47, v47
	s_nop 1
	v_mov_b32_dpp v32, v48 quad_perm:[1,0,3,2] row_mask:0xf bank_mask:0xf
	s_waitcnt lgkmcnt(0)
	v_add_f32_e32 v32, v48, v32
	global_load_dword v48, v[2:3], off offset:512
	s_nop 1
	v_mov_b32_dpp v33, v32 quad_perm:[2,3,0,1] row_mask:0xf bank_mask:0xf
	s_waitcnt lgkmcnt(0)
	v_add_f32_e32 v32, v32, v33
	s_nop 1
	v_mov_b32_dpp v33, v32 row_half_mirror row_mask:0xf bank_mask:0xf
	s_waitcnt lgkmcnt(0)
	v_add_f32_e32 v32, v32, v33
	s_nop 1
	v_mov_b32_dpp v33, v32 row_mirror row_mask:0xf bank_mask:0xf
	s_waitcnt lgkmcnt(0)
	v_add_f32_e32 v32, v32, v33
	v_mov_b32_e32 v33, v32
	s_nop 1
	v_permlane16_swap_b32_e32 v33, v32
	s_waitcnt lgkmcnt(0)
	v_add_f32_e32 v32, v32, v33
	v_fmamk_f32 v32, v32, 0x3b800000, v190
	v_mul_f32_e32 v33, 0x4f800000, v32
	v_cmp_gt_f32_e32 vcc, s56, v32
	s_nop 1
	v_cndmask_b32_e32 v79, v32, v33, vcc
	v_sqrt_f32_e32 v80, v79
	v_lshl_add_u32 v32, v193, 2, s42
	v_ashrrev_i32_e32 v33, 31, v32
	v_lshlrev_b64 v[32:33], 12, v[32:33]
	v_add_u32_e32 v81, -1, v80
	v_fma_f32 v90, -v81, v80, v79
	v_cmp_ge_f32_e64 s[0:1], 0, v90
	v_add_u32_e32 v90, 1, v80
	v_lshl_add_u64 v[32:33], s[44:45], 0, v[32:33]
	v_cndmask_b32_e64 v81, v80, v81, s[0:1]
	v_fma_f32 v80, -v90, v80, v79
	v_cmp_lt_f32_e64 s[0:1], 0, v80
	v_lshl_add_u64 v[32:33], s[26:27], 1, v[32:33]
	v_lshl_add_u64 v[32:33], v[178:179], 1, v[32:33]
	v_cndmask_b32_e64 v80, v81, v90, s[0:1]
	v_mul_f32_e32 v81, 0x37800000, v80
	v_cndmask_b32_e32 v80, v80, v81, vcc
	v_cmp_class_f32_e32 vcc, v79, v189
	s_nop 1
	v_cndmask_b32_e32 v79, v80, v79, vcc
	v_div_scale_f32 v80, s[0:1], v79, v79, s87
	v_rcp_f32_e32 v81, v80
	s_nop 0
	v_fma_f32 v90, -v80, v81, 1.0
	v_fmac_f32_e32 v81, v90, v81
	v_div_scale_f32 v90, vcc, s87, v79, s87
	v_mul_f32_e32 v91, v90, v81
	v_fma_f32 v92, -v80, v91, v90
	v_fmac_f32_e32 v91, v92, v81
	v_fma_f32 v80, -v80, v91, v90
	v_div_fmas_f32 v80, v80, v81, v91
	v_div_fixup_f32 v79, v80, v79, s87
	v_mul_f32_e32 v17, v17, v79
	s_waitcnt vmcnt(7)
	v_mul_f32_e32 v17, v62, v17
	v_bfe_u32 v62, v17, 16, 1
	v_add3_u32 v17, v17, v62, s88
	global_store_short_d16_hi v[32:33], v17, off offset:2048
	v_mul_f32_e32 v17, v31, v79
	s_waitcnt vmcnt(7)
	v_mul_f32_e32 v17, v64, v17
	v_bfe_u32 v31, v17, 16, 1
	v_add3_u32 v17, v17, v31, s88
	global_store_short_d16_hi v[32:33], v17, off offset:2112
	v_mul_f32_e32 v17, v49, v79
	s_waitcnt vmcnt(7)
	v_mul_f32_e32 v17, v65, v17
	v_bfe_u32 v31, v17, 16, 1
	v_add3_u32 v17, v17, v31, s88
	global_store_short_d16_hi v[32:33], v17, off offset:2176
	v_mul_f32_e32 v17, v60, v79
	s_waitcnt vmcnt(7)
	v_mul_f32_e32 v17, v75, v17
	v_bfe_u32 v31, v17, 16, 1
	v_add3_u32 v17, v17, v31, s88
	global_store_short_d16_hi v[32:33], v17, off offset:2240
	v_mul_f32_e32 v17, v61, v79
	s_waitcnt vmcnt(4)
	v_mul_f32_e32 v17, v48, v17
	v_bfe_u32 v31, v17, 16, 1
	v_add3_u32 v17, v17, v31, s88
	global_store_short_d16_hi v[32:33], v17, off offset:2304
	v_mul_f32_e32 v17, v63, v79
	v_mul_f32_e32 v17, v17, v76
	v_bfe_u32 v31, v17, 16, 1
	v_add3_u32 v17, v17, v31, s88
	global_store_short_d16_hi v[32:33], v17, off offset:2368
	v_mul_f32_e32 v17, v46, v79
	v_mul_f32_e32 v17, v17, v77
	v_bfe_u32 v31, v17, 16, 1
	v_add3_u32 v17, v17, v31, s88
	global_store_short_d16_hi v[32:33], v17, off offset:2432
	v_mul_f32_e32 v17, v47, v79
	v_mul_f32_e32 v17, v17, v78
	v_bfe_u32 v31, v17, 16, 1
	v_add3_u32 v17, v17, v31, s88
	global_store_short_d16_hi v[32:33], v17, off offset:2496
	v_lshl_add_u64 v[32:33], v[32:33], 0, s[12:13]
	v_add_u32_e32 v17, 0x400, v13
	ds_read2_b32 v[46:47], v17 offset1:32
	ds_read2_b32 v[48:49], v17 offset0:64 offset1:96
	global_load_dword v64, v[2:3], off
	global_load_dword v65, v[2:3], off offset:256
	global_load_dword v76, v[2:3], off offset:384
	global_load_dword v77, v[2:3], off offset:512
	global_load_dword v78, v[2:3], off offset:640
	global_load_dword v79, v[2:3], off offset:768
	s_waitcnt lgkmcnt(1)
	v_sub_f32_e32 v31, v171, v46
	v_sub_f32_e32 v60, v170, v47
	ds_read2_b32 v[46:47], v17 offset0:128 offset1:160
	v_mul_f32_e32 v61, v60, v60
	s_waitcnt lgkmcnt(1)
	v_sub_f32_e32 v62, v169, v48
	v_sub_f32_e32 v63, v168, v49
	ds_read2_b32 v[48:49], v17 offset0:192 offset1:224
	v_fmac_f32_e32 v61, v31, v31
	v_fmac_f32_e32 v61, v62, v62
	v_fmac_f32_e32 v61, v63, v63
	s_waitcnt lgkmcnt(1)
; #define LAS __attribute__((address_space(3)))
; __device__ __forceinline__ bf16_t f2bf(float f) { unsigned u = __float_as_uint(f); u += 0x7FFFu + ((u >> 16) & 1u); return (bf16_t)(u >> 16); }
; __device__ __forceinline__ void df_unit(LAS unsigned char* lds, const bf16_t* qkv, bf16_t* attout, const float* subg, int b_, int h_, int qb_, int wid, int) {
;     ...
;     if (jsel == 0) {
;         bf16_t* op = attout + (size_t)(b * SEQ + q0 + 4 * hi) * DM + 1024 + h * 256 + r32; const LAS float* xr = xb + (4 * hi) * 256 + r32;
; #pragma unroll
;         for (int r = 0; r < 16; ++r) { const int rowc = (r & 3) + 8 * (r >> 2); float ss = 0.f;
; #pragma unroll
;             for (int d = 0; d < 8; ++d) { o[d][r] -= xr[rowc * 256 + d * 32]; ss += o[d][r] * o[d][r]; }
;             ss += __shfl_xor(ss, 1); ss += __shfl_xor(ss, 2); ss += __shfl_xor(ss, 4); ss += __shfl_xor(ss, 8); ss += __shfl_xor(ss, 16);
;             const float rstd = (1.0f - LAMBDA_INIT) / sqrtf(ss * (1.0f / 256.0f) + SUBLN_EPS);
; #pragma unroll
;             for (int d = 0; d < 8; ++d) op[d * 32] = f2bf(o[d][r] * rstd * subg[d * 32 + r32]);
;             op += ((r & 3) == 3 ? 5 : 1) * DM; asm volatile("" : "+v"(op) :: "memory"); } }
	v_sub_f32_e32 v46, v167, v46
	v_fmac_f32_e32 v61, v46, v46
	v_sub_f32_e32 v17, v166, v47
	v_fmac_f32_e32 v61, v17, v17
	s_waitcnt lgkmcnt(0)
	v_sub_f32_e32 v48, v165, v48
	v_fmac_f32_e32 v61, v48, v48
	v_sub_f32_e32 v49, v164, v49
	v_fmac_f32_e32 v61, v49, v49
	s_nop 1
	v_mov_b32_dpp v75, v61 quad_perm:[1,0,3,2] row_mask:0xf bank_mask:0xf
	global_load_dword v47, v[2:3], off offset:128
	s_waitcnt lgkmcnt(0)
	v_add_f32_e32 v61, v61, v75
	s_nop 1
	v_mov_b32_dpp v75, v61 quad_perm:[2,3,0,1] row_mask:0xf bank_mask:0xf
	s_waitcnt lgkmcnt(0)
	v_add_f32_e32 v61, v61, v75
	s_nop 1
	v_mov_b32_dpp v75, v61 row_half_mirror row_mask:0xf bank_mask:0xf
	s_waitcnt lgkmcnt(0)
	v_add_f32_e32 v61, v61, v75
	s_nop 1
	v_mov_b32_dpp v75, v61 row_mirror row_mask:0xf bank_mask:0xf
	s_waitcnt lgkmcnt(0)
	v_add_f32_e32 v61, v61, v75
	global_load_dword v75, v[2:3], off offset:896
	v_mov_b32_e32 v80, v61
	s_nop 1
	v_permlane16_swap_b32_e32 v80, v61
	s_waitcnt lgkmcnt(0)
	v_add_f32_e32 v61, v61, v80
	v_fmamk_f32 v61, v61, 0x3b800000, v190
	v_mul_f32_e32 v80, 0x4f800000, v61
	v_cmp_gt_f32_e32 vcc, s56, v61
	s_nop 1
	v_cndmask_b32_e32 v61, v61, v80, vcc
	v_sqrt_f32_e32 v80, v61
	s_nop 0
	v_add_u32_e32 v81, -1, v80
	v_fma_f32 v90, -v81, v80, v61
	v_cmp_ge_f32_e64 s[0:1], 0, v90
	v_add_u32_e32 v90, 1, v80
	s_nop 0
	v_cndmask_b32_e64 v81, v80, v81, s[0:1]
	v_fma_f32 v80, -v90, v80, v61
	v_cmp_lt_f32_e64 s[0:1], 0, v80
	s_nop 1
	v_cndmask_b32_e64 v80, v81, v90, s[0:1]
	v_mul_f32_e32 v81, 0x37800000, v80
	v_cndmask_b32_e32 v80, v80, v81, vcc
	v_cmp_class_f32_e32 vcc, v61, v189
	s_nop 1
	v_cndmask_b32_e32 v61, v80, v61, vcc
	v_div_scale_f32 v80, s[0:1], v61, v61, s87
	v_rcp_f32_e32 v81, v80
	s_nop 0
	v_fma_f32 v90, -v80, v81, 1.0
	v_fmac_f32_e32 v81, v90, v81
	v_div_scale_f32 v90, vcc, s87, v61, s87
	v_mul_f32_e32 v91, v90, v81
	v_fma_f32 v92, -v80, v91, v90
	v_fmac_f32_e32 v91, v92, v81
	v_fma_f32 v80, -v80, v91, v90
	v_div_fmas_f32 v80, v80, v81, v91
	v_div_fixup_f32 v61, v80, v61, s87
	v_mul_f32_e32 v31, v31, v61
	s_waitcnt vmcnt(7)
	v_mul_f32_e32 v31, v64, v31
	v_bfe_u32 v64, v31, 16, 1
	v_add3_u32 v31, v31, v64, s88
	flat_store_short_d16_hi v[32:33], v31
	v_mul_f32_e32 v31, v60, v61
	v_mul_f32_e32 v17, v17, v61
	s_waitcnt vmcnt(0)
	v_mul_f32_e32 v31, v47, v31
	v_bfe_u32 v47, v31, 16, 1
	v_add3_u32 v31, v31, v47, s88
	flat_store_short_d16_hi v[32:33], v31 offset:64
	v_mul_f32_e32 v31, v62, v61
	v_mul_f32_e32 v31, v65, v31
	v_bfe_u32 v47, v31, 16, 1
	v_add3_u32 v31, v31, v47, s88
	flat_store_short_d16_hi v[32:33], v31 offset:128
	v_mul_f32_e32 v31, v63, v61
	v_mul_f32_e32 v31, v76, v31
	v_bfe_u32 v47, v31, 16, 1
	v_add3_u32 v31, v31, v47, s88
	flat_store_short_d16_hi v[32:33], v31 offset:192
	v_mul_f32_e32 v31, v46, v61
	v_mul_f32_e32 v31, v77, v31
	v_bfe_u32 v46, v31, 16, 1
	v_add3_u32 v31, v31, v46, s88
	v_mul_f32_e32 v17, v17, v78
	flat_store_short_d16_hi v[32:33], v31 offset:256
	v_bfe_u32 v31, v17, 16, 1
	v_add3_u32 v17, v17, v31, s88
	flat_store_short_d16_hi v[32:33], v17 offset:320
	v_mul_f32_e32 v17, v48, v61
	v_mul_f32_e32 v17, v17, v79
	v_bfe_u32 v31, v17, 16, 1
	v_add3_u32 v17, v17, v31, s88
	flat_store_short_d16_hi v[32:33], v17 offset:384
	v_mul_f32_e32 v17, v49, v61
	v_mul_f32_e32 v17, v17, v75
	v_bfe_u32 v31, v17, 16, 1
	v_add3_u32 v17, v17, v31, s88
	flat_store_short_d16_hi v[32:33], v17 offset:448
	v_lshl_add_u64 v[32:33], v[32:33], 0, s[20:21]
	v_add_u32_e32 v17, 0x800, v13
	ds_read2_b32 v[46:47], v17 offset1:32
	ds_read2_b32 v[48:49], v17 offset0:64 offset1:96
	global_load_dword v64, v[2:3], off
	global_load_dword v65, v[2:3], off offset:256
	global_load_dword v76, v[2:3], off offset:384
	global_load_dword v77, v[2:3], off offset:512
	global_load_dword v78, v[2:3], off offset:640
	global_load_dword v79, v[2:3], off offset:768
	s_waitcnt lgkmcnt(0)
	v_sub_f32_e32 v31, v163, v46
	v_sub_f32_e32 v60, v162, v47
	ds_read2_b32 v[46:47], v17 offset0:128 offset1:160
	v_mul_f32_e32 v61, v60, v60
	v_sub_f32_e32 v62, v161, v48
	v_sub_f32_e32 v63, v160, v49
	ds_read2_b32 v[48:49], v17 offset0:192 offset1:224
	v_fmac_f32_e32 v61, v31, v31
	v_fmac_f32_e32 v61, v62, v62
	v_fmac_f32_e32 v61, v63, v63
	s_waitcnt lgkmcnt(0)
	v_sub_f32_e32 v46, v159, v46
	v_fmac_f32_e32 v61, v46, v46
	v_sub_f32_e32 v17, v158, v47
	v_fmac_f32_e32 v61, v17, v17
	v_sub_f32_e32 v48, v157, v48
	v_fmac_f32_e32 v61, v48, v48
	v_sub_f32_e32 v49, v156, v49
	v_fmac_f32_e32 v61, v49, v49
	s_nop 1
	v_mov_b32_dpp v75, v61 quad_perm:[1,0,3,2] row_mask:0xf bank_mask:0xf
	global_load_dword v47, v[2:3], off offset:128
	s_waitcnt lgkmcnt(0)
	v_add_f32_e32 v61, v61, v75
	s_nop 1
	v_mov_b32_dpp v75, v61 quad_perm:[2,3,0,1] row_mask:0xf bank_mask:0xf
	s_waitcnt lgkmcnt(0)
	v_add_f32_e32 v61, v61, v75
	s_nop 1
	v_mov_b32_dpp v75, v61 row_half_mirror row_mask:0xf bank_mask:0xf
	s_waitcnt lgkmcnt(0)
	v_add_f32_e32 v61, v61, v75
	s_nop 1
	v_mov_b32_dpp v75, v61 row_mirror row_mask:0xf bank_mask:0xf
	s_waitcnt lgkmcnt(0)
	v_add_f32_e32 v61, v61, v75
	global_load_dword v75, v[2:3], off offset:896
	v_mov_b32_e32 v80, v61
	s_nop 1
	v_permlane16_swap_b32_e32 v80, v61
	s_waitcnt lgkmcnt(0)
; #define LAS __attribute__((address_space(3)))
; __device__ __forceinline__ bf16_t f2bf(float f) { unsigned u = __float_as_uint(f); u += 0x7FFFu + ((u >> 16) & 1u); return (bf16_t)(u >> 16); }
; __device__ __forceinline__ void df_unit(LAS unsigned char* lds, const bf16_t* qkv, bf16_t* attout, const float* subg, int b_, int h_, int qb_, int wid, int) {
;     ...
;     if (jsel == 0) {
;         bf16_t* op = attout + (size_t)(b * SEQ + q0 + 4 * hi) * DM + 1024 + h * 256 + r32; const LAS float* xr = xb + (4 * hi) * 256 + r32;
; #pragma unroll
;         for (int r = 0; r < 16; ++r) { const int rowc = (r & 3) + 8 * (r >> 2); float ss = 0.f;
; #pragma unroll
;             for (int d = 0; d < 8; ++d) { o[d][r] -= xr[rowc * 256 + d * 32]; ss += o[d][r] * o[d][r]; }
;             ss += __shfl_xor(ss, 1); ss += __shfl_xor(ss, 2); ss += __shfl_xor(ss, 4); ss += __shfl_xor(ss, 8); ss += __shfl_xor(ss, 16);
;             const float rstd = (1.0f - LAMBDA_INIT) / sqrtf(ss * (1.0f / 256.0f) + SUBLN_EPS);
; #pragma unroll
;             for (int d = 0; d < 8; ++d) op[d * 32] = f2bf(o[d][r] * rstd * subg[d * 32 + r32]);
;             op += ((r & 3) == 3 ? 5 : 1) * DM; asm volatile("" : "+v"(op) :: "memory"); } }
	v_add_f32_e32 v61, v61, v80
	v_fmamk_f32 v61, v61, 0x3b800000, v190
	v_mul_f32_e32 v80, 0x4f800000, v61
	v_cmp_gt_f32_e32 vcc, s56, v61
	s_nop 1
	v_cndmask_b32_e32 v61, v61, v80, vcc
	v_sqrt_f32_e32 v80, v61
	s_nop 0
	v_add_u32_e32 v81, -1, v80
	v_fma_f32 v90, -v81, v80, v61
	v_cmp_ge_f32_e64 s[0:1], 0, v90
	v_add_u32_e32 v90, 1, v80
	s_nop 0
	v_cndmask_b32_e64 v81, v80, v81, s[0:1]
	v_fma_f32 v80, -v90, v80, v61
	v_cmp_lt_f32_e64 s[0:1], 0, v80
	s_nop 1
	v_cndmask_b32_e64 v80, v81, v90, s[0:1]
	v_mul_f32_e32 v81, 0x37800000, v80
	v_cndmask_b32_e32 v80, v80, v81, vcc
	v_cmp_class_f32_e32 vcc, v61, v189
	s_nop 1
	v_cndmask_b32_e32 v61, v80, v61, vcc
	v_div_scale_f32 v80, s[0:1], v61, v61, s87
	v_rcp_f32_e32 v81, v80
	s_nop 0
	v_fma_f32 v90, -v80, v81, 1.0
	v_fmac_f32_e32 v81, v90, v81
	v_div_scale_f32 v90, vcc, s87, v61, s87
	v_mul_f32_e32 v91, v90, v81
	v_fma_f32 v92, -v80, v91, v90
	v_fmac_f32_e32 v91, v92, v81
	v_fma_f32 v80, -v80, v91, v90
	v_div_fmas_f32 v80, v80, v81, v91
	v_div_fixup_f32 v61, v80, v61, s87
	v_mul_f32_e32 v31, v31, v61
	s_waitcnt vmcnt(0)
	v_mul_f32_e32 v31, v64, v31
	v_bfe_u32 v64, v31, 16, 1
	v_add3_u32 v31, v31, v64, s88
	flat_store_short_d16_hi v[32:33], v31
	v_mul_f32_e32 v31, v60, v61
	v_mul_f32_e32 v17, v17, v61
	v_mul_f32_e32 v31, v47, v31
	v_bfe_u32 v47, v31, 16, 1
	v_add3_u32 v31, v31, v47, s88
	flat_store_short_d16_hi v[32:33], v31 offset:64
	v_mul_f32_e32 v31, v62, v61
	v_mul_f32_e32 v31, v65, v31
	v_bfe_u32 v47, v31, 16, 1
	v_add3_u32 v31, v31, v47, s88
	flat_store_short_d16_hi v[32:33], v31 offset:128
	v_mul_f32_e32 v31, v63, v61
	v_mul_f32_e32 v31, v76, v31
	v_bfe_u32 v47, v31, 16, 1
	v_add3_u32 v31, v31, v47, s88
	flat_store_short_d16_hi v[32:33], v31 offset:192
	v_mul_f32_e32 v31, v46, v61
	v_mul_f32_e32 v31, v77, v31
	v_bfe_u32 v46, v31, 16, 1
	v_add3_u32 v31, v31, v46, s88
	v_mul_f32_e32 v17, v17, v78
	flat_store_short_d16_hi v[32:33], v31 offset:256
	v_bfe_u32 v31, v17, 16, 1
	v_add3_u32 v17, v17, v31, s88
	flat_store_short_d16_hi v[32:33], v17 offset:320
	v_mul_f32_e32 v17, v48, v61
	v_mul_f32_e32 v17, v17, v79
	v_bfe_u32 v31, v17, 16, 1
	v_add3_u32 v17, v17, v31, s88
	flat_store_short_d16_hi v[32:33], v17 offset:384
	v_mul_f32_e32 v17, v49, v61
	v_mul_f32_e32 v17, v17, v75
	v_bfe_u32 v31, v17, 16, 1
	v_add3_u32 v17, v17, v31, s88
	flat_store_short_d16_hi v[32:33], v17 offset:448
	v_lshl_add_u64 v[32:33], v[32:33], 0, s[20:21]
	v_add_u32_e32 v17, 0xc00, v13
	ds_read2_b32 v[46:47], v17 offset1:32
	ds_read2_b32 v[48:49], v17 offset0:64 offset1:96
	global_load_dword v64, v[2:3], off
	global_load_dword v65, v[2:3], off offset:256
	global_load_dword v76, v[2:3], off offset:384
	global_load_dword v77, v[2:3], off offset:512
	global_load_dword v78, v[2:3], off offset:640
	global_load_dword v79, v[2:3], off offset:768
	s_waitcnt lgkmcnt(0)
	v_sub_f32_e32 v31, v155, v46
	v_sub_f32_e32 v60, v154, v47
	ds_read2_b32 v[46:47], v17 offset0:128 offset1:160
	v_mul_f32_e32 v61, v60, v60
	v_sub_f32_e32 v62, v153, v48
	v_sub_f32_e32 v63, v152, v49
	ds_read2_b32 v[48:49], v17 offset0:192 offset1:224
	v_fmac_f32_e32 v61, v31, v31
	v_fmac_f32_e32 v61, v62, v62
	v_fmac_f32_e32 v61, v63, v63
	s_waitcnt lgkmcnt(0)
	v_sub_f32_e32 v46, v151, v46
	v_fmac_f32_e32 v61, v46, v46
	v_sub_f32_e32 v17, v150, v47
	v_fmac_f32_e32 v61, v17, v17
	v_sub_f32_e32 v48, v149, v48
	v_fmac_f32_e32 v61, v48, v48
	v_sub_f32_e32 v49, v148, v49
	v_fmac_f32_e32 v61, v49, v49
	s_nop 1
	v_mov_b32_dpp v75, v61 quad_perm:[1,0,3,2] row_mask:0xf bank_mask:0xf
	global_load_dword v47, v[2:3], off offset:128
	s_waitcnt lgkmcnt(0)
	v_add_f32_e32 v61, v61, v75
	s_nop 1
	v_mov_b32_dpp v75, v61 quad_perm:[2,3,0,1] row_mask:0xf bank_mask:0xf
	s_waitcnt lgkmcnt(0)
	v_add_f32_e32 v61, v61, v75
	s_nop 1
	v_mov_b32_dpp v75, v61 row_half_mirror row_mask:0xf bank_mask:0xf
	s_waitcnt lgkmcnt(0)
	v_add_f32_e32 v61, v61, v75
	s_nop 1
	v_mov_b32_dpp v75, v61 row_mirror row_mask:0xf bank_mask:0xf
	s_waitcnt lgkmcnt(0)
	v_add_f32_e32 v61, v61, v75
	global_load_dword v75, v[2:3], off offset:896
	v_mov_b32_e32 v80, v61
	s_nop 1
	v_permlane16_swap_b32_e32 v80, v61
	s_waitcnt lgkmcnt(0)
	v_add_f32_e32 v61, v61, v80
	v_fmamk_f32 v61, v61, 0x3b800000, v190
	v_mul_f32_e32 v80, 0x4f800000, v61
	v_cmp_gt_f32_e32 vcc, s56, v61
	s_nop 1
	v_cndmask_b32_e32 v61, v61, v80, vcc
	v_sqrt_f32_e32 v80, v61
	s_nop 0
	v_add_u32_e32 v81, -1, v80
	v_fma_f32 v90, -v81, v80, v61
	v_cmp_ge_f32_e64 s[0:1], 0, v90
	v_add_u32_e32 v90, 1, v80
	s_nop 0
	v_cndmask_b32_e64 v81, v80, v81, s[0:1]
	v_fma_f32 v80, -v90, v80, v61
	v_cmp_lt_f32_e64 s[0:1], 0, v80
	s_nop 1
	v_cndmask_b32_e64 v80, v81, v90, s[0:1]
	v_mul_f32_e32 v81, 0x37800000, v80
	v_cndmask_b32_e32 v80, v80, v81, vcc
	v_cmp_class_f32_e32 vcc, v61, v189
	s_nop 1
	v_cndmask_b32_e32 v61, v80, v61, vcc
	v_div_scale_f32 v80, s[0:1], v61, v61, s87
	v_rcp_f32_e32 v81, v80
	s_nop 0
	v_fma_f32 v90, -v80, v81, 1.0
	v_fmac_f32_e32 v81, v90, v81
	v_div_scale_f32 v90, vcc, s87, v61, s87
	v_mul_f32_e32 v91, v90, v81
	v_fma_f32 v92, -v80, v91, v90
	v_fmac_f32_e32 v91, v92, v81
	v_fma_f32 v80, -v80, v91, v90
	v_div_fmas_f32 v80, v80, v81, v91
	v_div_fixup_f32 v61, v80, v61, s87
	v_mul_f32_e32 v31, v31, v61
	s_waitcnt vmcnt(0)
; #define LAS __attribute__((address_space(3)))
; __device__ __forceinline__ bf16_t f2bf(float f) { unsigned u = __float_as_uint(f); u += 0x7FFFu + ((u >> 16) & 1u); return (bf16_t)(u >> 16); }
; __device__ __forceinline__ void df_unit(LAS unsigned char* lds, const bf16_t* qkv, bf16_t* attout, const float* subg, int b_, int h_, int qb_, int wid, int) {
;     ...
;     if (jsel == 0) {
;         bf16_t* op = attout + (size_t)(b * SEQ + q0 + 4 * hi) * DM + 1024 + h * 256 + r32; const LAS float* xr = xb + (4 * hi) * 256 + r32;
; #pragma unroll
;         for (int r = 0; r < 16; ++r) { const int rowc = (r & 3) + 8 * (r >> 2); float ss = 0.f;
; #pragma unroll
;             for (int d = 0; d < 8; ++d) { o[d][r] -= xr[rowc * 256 + d * 32]; ss += o[d][r] * o[d][r]; }
;             ss += __shfl_xor(ss, 1); ss += __shfl_xor(ss, 2); ss += __shfl_xor(ss, 4); ss += __shfl_xor(ss, 8); ss += __shfl_xor(ss, 16);
;             const float rstd = (1.0f - LAMBDA_INIT) / sqrtf(ss * (1.0f / 256.0f) + SUBLN_EPS);
; #pragma unroll
;             for (int d = 0; d < 8; ++d) op[d * 32] = f2bf(o[d][r] * rstd * subg[d * 32 + r32]);
;             op += ((r & 3) == 3 ? 5 : 1) * DM; asm volatile("" : "+v"(op) :: "memory"); } }
	v_mul_f32_e32 v31, v64, v31
	v_bfe_u32 v64, v31, 16, 1
	v_add3_u32 v31, v31, v64, s88
	flat_store_short_d16_hi v[32:33], v31
	v_mul_f32_e32 v31, v60, v61
	v_mul_f32_e32 v17, v17, v61
	v_mul_f32_e32 v31, v47, v31
	v_bfe_u32 v47, v31, 16, 1
	v_add3_u32 v31, v31, v47, s88
	flat_store_short_d16_hi v[32:33], v31 offset:64
	v_mul_f32_e32 v31, v62, v61
	v_mul_f32_e32 v31, v65, v31
	v_bfe_u32 v47, v31, 16, 1
	v_add3_u32 v31, v31, v47, s88
	flat_store_short_d16_hi v[32:33], v31 offset:128
	v_mul_f32_e32 v31, v63, v61
	v_mul_f32_e32 v31, v76, v31
	v_bfe_u32 v47, v31, 16, 1
	v_add3_u32 v31, v31, v47, s88
	flat_store_short_d16_hi v[32:33], v31 offset:192
	v_mul_f32_e32 v31, v46, v61
	v_mul_f32_e32 v31, v77, v31
	v_bfe_u32 v46, v31, 16, 1
	v_add3_u32 v31, v31, v46, s88
	v_mul_f32_e32 v17, v17, v78
	flat_store_short_d16_hi v[32:33], v31 offset:256
	v_bfe_u32 v31, v17, 16, 1
	v_add3_u32 v17, v17, v31, s88
	flat_store_short_d16_hi v[32:33], v17 offset:320
	v_mul_f32_e32 v17, v48, v61
	v_mul_f32_e32 v17, v17, v79
	v_bfe_u32 v31, v17, 16, 1
	v_add3_u32 v17, v17, v31, s88
	flat_store_short_d16_hi v[32:33], v17 offset:384
	v_mul_f32_e32 v17, v49, v61
	v_mul_f32_e32 v17, v17, v75
	v_bfe_u32 v31, v17, 16, 1
	v_add3_u32 v17, v17, v31, s88
	flat_store_short_d16_hi v[32:33], v17 offset:448
	v_lshl_add_u64 v[32:33], v[32:33], 0, s[22:23]
	v_add_u32_e32 v17, 0x2000, v13
	ds_read2_b32 v[46:47], v17 offset1:32
	ds_read2_b32 v[48:49], v17 offset0:64 offset1:96
	global_load_dword v64, v[2:3], off
	global_load_dword v65, v[2:3], off offset:256
	global_load_dword v76, v[2:3], off offset:384
	global_load_dword v77, v[2:3], off offset:512
	global_load_dword v78, v[2:3], off offset:640
	global_load_dword v79, v[2:3], off offset:768
	s_waitcnt lgkmcnt(0)
	v_sub_f32_e32 v31, v147, v46
	v_sub_f32_e32 v60, v146, v47
	ds_read2_b32 v[46:47], v17 offset0:128 offset1:160
	v_mul_f32_e32 v61, v60, v60
	v_sub_f32_e32 v62, v145, v48
	v_sub_f32_e32 v63, v144, v49
	ds_read2_b32 v[48:49], v17 offset0:192 offset1:224
	v_fmac_f32_e32 v61, v31, v31
	v_fmac_f32_e32 v61, v62, v62
	v_fmac_f32_e32 v61, v63, v63
	s_waitcnt lgkmcnt(0)
	v_sub_f32_e32 v46, v143, v46
	v_fmac_f32_e32 v61, v46, v46
	v_sub_f32_e32 v17, v142, v47
	v_fmac_f32_e32 v61, v17, v17
	v_sub_f32_e32 v48, v141, v48
	v_fmac_f32_e32 v61, v48, v48
	v_sub_f32_e32 v49, v140, v49
	v_fmac_f32_e32 v61, v49, v49
	s_nop 1
	v_mov_b32_dpp v75, v61 quad_perm:[1,0,3,2] row_mask:0xf bank_mask:0xf
	global_load_dword v47, v[2:3], off offset:128
	s_waitcnt lgkmcnt(0)
	v_add_f32_e32 v61, v61, v75
	s_nop 1
	v_mov_b32_dpp v75, v61 quad_perm:[2,3,0,1] row_mask:0xf bank_mask:0xf
	s_waitcnt lgkmcnt(0)
	v_add_f32_e32 v61, v61, v75
	s_nop 1
	v_mov_b32_dpp v75, v61 row_half_mirror row_mask:0xf bank_mask:0xf
	s_waitcnt lgkmcnt(0)
	v_add_f32_e32 v61, v61, v75
	s_nop 1
	v_mov_b32_dpp v75, v61 row_mirror row_mask:0xf bank_mask:0xf
	s_waitcnt lgkmcnt(0)
	v_add_f32_e32 v61, v61, v75
	global_load_dword v75, v[2:3], off offset:896
	v_mov_b32_e32 v80, v61
	s_nop 1
	v_permlane16_swap_b32_e32 v80, v61
	s_waitcnt lgkmcnt(0)
	v_add_f32_e32 v61, v61, v80
	v_fmamk_f32 v61, v61, 0x3b800000, v190
	v_mul_f32_e32 v80, 0x4f800000, v61
	v_cmp_gt_f32_e32 vcc, s56, v61
	s_nop 1
	v_cndmask_b32_e32 v61, v61, v80, vcc
	v_sqrt_f32_e32 v80, v61
	s_nop 0
	v_add_u32_e32 v81, -1, v80
	v_fma_f32 v90, -v81, v80, v61
	v_cmp_ge_f32_e64 s[0:1], 0, v90
	v_add_u32_e32 v90, 1, v80
	s_nop 0
	v_cndmask_b32_e64 v81, v80, v81, s[0:1]
	v_fma_f32 v80, -v90, v80, v61
	v_cmp_lt_f32_e64 s[0:1], 0, v80
	s_nop 1
	v_cndmask_b32_e64 v80, v81, v90, s[0:1]
	v_mul_f32_e32 v81, 0x37800000, v80
	v_cndmask_b32_e32 v80, v80, v81, vcc
	v_cmp_class_f32_e32 vcc, v61, v189
	s_nop 1
	v_cndmask_b32_e32 v61, v80, v61, vcc
	v_div_scale_f32 v80, s[0:1], v61, v61, s87
	v_rcp_f32_e32 v81, v80
	s_nop 0
	v_fma_f32 v90, -v80, v81, 1.0
	v_fmac_f32_e32 v81, v90, v81
	v_div_scale_f32 v90, vcc, s87, v61, s87
	v_mul_f32_e32 v91, v90, v81
	v_fma_f32 v92, -v80, v91, v90
	v_fmac_f32_e32 v91, v92, v81
	v_fma_f32 v80, -v80, v91, v90
	v_div_fmas_f32 v80, v80, v81, v91
	v_div_fixup_f32 v61, v80, v61, s87
	v_mul_f32_e32 v31, v31, v61
	s_waitcnt vmcnt(0)
	v_mul_f32_e32 v31, v64, v31
	v_bfe_u32 v64, v31, 16, 1
	v_add3_u32 v31, v31, v64, s88
	flat_store_short_d16_hi v[32:33], v31
	v_mul_f32_e32 v31, v60, v61
	v_mul_f32_e32 v17, v17, v61
	v_mul_f32_e32 v31, v47, v31
	v_bfe_u32 v47, v31, 16, 1
	v_add3_u32 v31, v31, v47, s88
	flat_store_short_d16_hi v[32:33], v31 offset:64
	v_mul_f32_e32 v31, v62, v61
	v_mul_f32_e32 v31, v65, v31
	v_bfe_u32 v47, v31, 16, 1
	v_add3_u32 v31, v31, v47, s88
	flat_store_short_d16_hi v[32:33], v31 offset:128
	v_mul_f32_e32 v31, v63, v61
	v_mul_f32_e32 v31, v76, v31
	v_bfe_u32 v47, v31, 16, 1
	v_add3_u32 v31, v31, v47, s88
	flat_store_short_d16_hi v[32:33], v31 offset:192
	v_mul_f32_e32 v31, v46, v61
	v_mul_f32_e32 v31, v77, v31
	v_bfe_u32 v46, v31, 16, 1
	v_add3_u32 v31, v31, v46, s88
	v_mul_f32_e32 v17, v17, v78
	flat_store_short_d16_hi v[32:33], v31 offset:256
	v_bfe_u32 v31, v17, 16, 1
	v_add3_u32 v17, v17, v31, s88
	flat_store_short_d16_hi v[32:33], v17 offset:320
	v_mul_f32_e32 v17, v48, v61
	v_mul_f32_e32 v17, v17, v79
	v_bfe_u32 v31, v17, 16, 1
	v_add3_u32 v17, v17, v31, s88
	flat_store_short_d16_hi v[32:33], v17 offset:384
	v_mul_f32_e32 v17, v49, v61
	v_mul_f32_e32 v17, v17, v75
	v_bfe_u32 v31, v17, 16, 1
	v_add3_u32 v17, v17, v31, s88
	flat_store_short_d16_hi v[32:33], v17 offset:448
	v_lshl_add_u64 v[32:33], v[32:33], 0, s[20:21]
	v_add_u32_e32 v17, 0x2400, v13
	ds_read2_b32 v[46:47], v17 offset1:32
	ds_read2_b32 v[48:49], v17 offset0:64 offset1:96
	global_load_dword v64, v[2:3], off
	global_load_dword v65, v[2:3], off offset:256
	global_load_dword v76, v[2:3], off offset:384
	global_load_dword v77, v[2:3], off offset:512
	global_load_dword v78, v[2:3], off offset:640
	global_load_dword v79, v[2:3], off offset:768
	s_waitcnt lgkmcnt(0)
; #define LAS __attribute__((address_space(3)))
; __device__ __forceinline__ bf16_t f2bf(float f) { unsigned u = __float_as_uint(f); u += 0x7FFFu + ((u >> 16) & 1u); return (bf16_t)(u >> 16); }
; __device__ __forceinline__ void df_unit(LAS unsigned char* lds, const bf16_t* qkv, bf16_t* attout, const float* subg, int b_, int h_, int qb_, int wid, int) {
;     ...
;     if (jsel == 0) {
;         bf16_t* op = attout + (size_t)(b * SEQ + q0 + 4 * hi) * DM + 1024 + h * 256 + r32; const LAS float* xr = xb + (4 * hi) * 256 + r32;
; #pragma unroll
;         for (int r = 0; r < 16; ++r) { const int rowc = (r & 3) + 8 * (r >> 2); float ss = 0.f;
; #pragma unroll
;             for (int d = 0; d < 8; ++d) { o[d][r] -= xr[rowc * 256 + d * 32]; ss += o[d][r] * o[d][r]; }
;             ss += __shfl_xor(ss, 1); ss += __shfl_xor(ss, 2); ss += __shfl_xor(ss, 4); ss += __shfl_xor(ss, 8); ss += __shfl_xor(ss, 16);
;             const float rstd = (1.0f - LAMBDA_INIT) / sqrtf(ss * (1.0f / 256.0f) + SUBLN_EPS);
; #pragma unroll
;             for (int d = 0; d < 8; ++d) op[d * 32] = f2bf(o[d][r] * rstd * subg[d * 32 + r32]);
;             op += ((r & 3) == 3 ? 5 : 1) * DM; asm volatile("" : "+v"(op) :: "memory"); } }
	v_sub_f32_e32 v31, v139, v46
	v_sub_f32_e32 v60, v138, v47
	ds_read2_b32 v[46:47], v17 offset0:128 offset1:160
	v_mul_f32_e32 v61, v60, v60
	v_sub_f32_e32 v62, v137, v48
	v_sub_f32_e32 v63, v136, v49
	ds_read2_b32 v[48:49], v17 offset0:192 offset1:224
	v_fmac_f32_e32 v61, v31, v31
	v_fmac_f32_e32 v61, v62, v62
	v_fmac_f32_e32 v61, v63, v63
	s_waitcnt lgkmcnt(0)
	v_sub_f32_e32 v46, v135, v46
	v_fmac_f32_e32 v61, v46, v46
	v_sub_f32_e32 v17, v134, v47
	v_fmac_f32_e32 v61, v17, v17
	v_sub_f32_e32 v48, v133, v48
	v_fmac_f32_e32 v61, v48, v48
	v_sub_f32_e32 v49, v132, v49
	v_fmac_f32_e32 v61, v49, v49
	s_nop 1
	v_mov_b32_dpp v75, v61 quad_perm:[1,0,3,2] row_mask:0xf bank_mask:0xf
	global_load_dword v47, v[2:3], off offset:128
	s_waitcnt lgkmcnt(0)
	v_add_f32_e32 v61, v61, v75
	s_nop 1
	v_mov_b32_dpp v75, v61 quad_perm:[2,3,0,1] row_mask:0xf bank_mask:0xf
	s_waitcnt lgkmcnt(0)
	v_add_f32_e32 v61, v61, v75
	s_nop 1
	v_mov_b32_dpp v75, v61 row_half_mirror row_mask:0xf bank_mask:0xf
	s_waitcnt lgkmcnt(0)
	v_add_f32_e32 v61, v61, v75
	s_nop 1
	v_mov_b32_dpp v75, v61 row_mirror row_mask:0xf bank_mask:0xf
	s_waitcnt lgkmcnt(0)
	v_add_f32_e32 v61, v61, v75
	global_load_dword v75, v[2:3], off offset:896
	v_mov_b32_e32 v80, v61
	s_nop 1
	v_permlane16_swap_b32_e32 v80, v61
	s_waitcnt lgkmcnt(0)
	v_add_f32_e32 v61, v61, v80
	v_fmamk_f32 v61, v61, 0x3b800000, v190
	v_mul_f32_e32 v80, 0x4f800000, v61
	v_cmp_gt_f32_e32 vcc, s56, v61
	s_nop 1
	v_cndmask_b32_e32 v61, v61, v80, vcc
	v_sqrt_f32_e32 v80, v61
	s_nop 0
	v_add_u32_e32 v81, -1, v80
	v_fma_f32 v90, -v81, v80, v61
	v_cmp_ge_f32_e64 s[0:1], 0, v90
	v_add_u32_e32 v90, 1, v80
	s_nop 0
	v_cndmask_b32_e64 v81, v80, v81, s[0:1]
	v_fma_f32 v80, -v90, v80, v61
	v_cmp_lt_f32_e64 s[0:1], 0, v80
	s_nop 1
	v_cndmask_b32_e64 v80, v81, v90, s[0:1]
	v_mul_f32_e32 v81, 0x37800000, v80
	v_cndmask_b32_e32 v80, v80, v81, vcc
	v_cmp_class_f32_e32 vcc, v61, v189
	s_nop 1
	v_cndmask_b32_e32 v61, v80, v61, vcc
	v_div_scale_f32 v80, s[0:1], v61, v61, s87
	v_rcp_f32_e32 v81, v80
	s_nop 0
	v_fma_f32 v90, -v80, v81, 1.0
	v_fmac_f32_e32 v81, v90, v81
	v_div_scale_f32 v90, vcc, s87, v61, s87
	v_mul_f32_e32 v91, v90, v81
	v_fma_f32 v92, -v80, v91, v90
	v_fmac_f32_e32 v91, v92, v81
	v_fma_f32 v80, -v80, v91, v90
	v_div_fmas_f32 v80, v80, v81, v91
	v_div_fixup_f32 v61, v80, v61, s87
	v_mul_f32_e32 v31, v31, v61
	s_waitcnt vmcnt(0)
	v_mul_f32_e32 v31, v64, v31
	v_bfe_u32 v64, v31, 16, 1
	v_add3_u32 v31, v31, v64, s88
	flat_store_short_d16_hi v[32:33], v31
	v_mul_f32_e32 v31, v60, v61
	v_mul_f32_e32 v17, v17, v61
	v_mul_f32_e32 v31, v47, v31
	v_bfe_u32 v47, v31, 16, 1
	v_add3_u32 v31, v31, v47, s88
	flat_store_short_d16_hi v[32:33], v31 offset:64
	v_mul_f32_e32 v31, v62, v61
	v_mul_f32_e32 v31, v65, v31
	v_bfe_u32 v47, v31, 16, 1
	v_add3_u32 v31, v31, v47, s88
	flat_store_short_d16_hi v[32:33], v31 offset:128
	v_mul_f32_e32 v31, v63, v61
	v_mul_f32_e32 v31, v76, v31
	v_bfe_u32 v47, v31, 16, 1
	v_add3_u32 v31, v31, v47, s88
	flat_store_short_d16_hi v[32:33], v31 offset:192
	v_mul_f32_e32 v31, v46, v61
	v_mul_f32_e32 v31, v77, v31
	v_bfe_u32 v46, v31, 16, 1
	v_add3_u32 v31, v31, v46, s88
	v_mul_f32_e32 v17, v17, v78
	flat_store_short_d16_hi v[32:33], v31 offset:256
	v_bfe_u32 v31, v17, 16, 1
	v_add3_u32 v17, v17, v31, s88
	flat_store_short_d16_hi v[32:33], v17 offset:320
	v_mul_f32_e32 v17, v48, v61
	v_mul_f32_e32 v17, v17, v79
	v_bfe_u32 v31, v17, 16, 1
	v_add3_u32 v17, v17, v31, s88
	flat_store_short_d16_hi v[32:33], v17 offset:384
	v_mul_f32_e32 v17, v49, v61
	v_mul_f32_e32 v17, v17, v75
	v_bfe_u32 v31, v17, 16, 1
	v_add3_u32 v17, v17, v31, s88
	flat_store_short_d16_hi v[32:33], v17 offset:448
	v_lshl_add_u64 v[32:33], v[32:33], 0, s[20:21]
	v_add_u32_e32 v17, 0x2800, v13
	ds_read2_b32 v[46:47], v17 offset1:32
	ds_read2_b32 v[48:49], v17 offset0:64 offset1:96
	global_load_dword v64, v[2:3], off
	global_load_dword v65, v[2:3], off offset:256
	global_load_dword v76, v[2:3], off offset:384
	global_load_dword v77, v[2:3], off offset:512
	global_load_dword v78, v[2:3], off offset:640
	global_load_dword v79, v[2:3], off offset:768
	s_waitcnt lgkmcnt(0)
	v_sub_f32_e32 v31, v131, v46
	v_sub_f32_e32 v60, v130, v47
	ds_read2_b32 v[46:47], v17 offset0:128 offset1:160
	v_mul_f32_e32 v61, v60, v60
	v_sub_f32_e32 v62, v119, v48
	v_sub_f32_e32 v63, v118, v49
	ds_read2_b32 v[48:49], v17 offset0:192 offset1:224
	v_fmac_f32_e32 v61, v31, v31
	v_fmac_f32_e32 v61, v62, v62
	v_fmac_f32_e32 v61, v63, v63
	s_waitcnt lgkmcnt(0)
	v_sub_f32_e32 v46, v117, v46
	v_fmac_f32_e32 v61, v46, v46
	v_sub_f32_e32 v17, v116, v47
	v_fmac_f32_e32 v61, v17, v17
	v_sub_f32_e32 v48, v115, v48
	v_fmac_f32_e32 v61, v48, v48
	v_sub_f32_e32 v49, v114, v49
	v_fmac_f32_e32 v61, v49, v49
	s_nop 1
	v_mov_b32_dpp v75, v61 quad_perm:[1,0,3,2] row_mask:0xf bank_mask:0xf
	global_load_dword v47, v[2:3], off offset:128
	s_waitcnt lgkmcnt(0)
	v_add_f32_e32 v61, v61, v75
	s_nop 1
	v_mov_b32_dpp v75, v61 quad_perm:[2,3,0,1] row_mask:0xf bank_mask:0xf
	s_waitcnt lgkmcnt(0)
	v_add_f32_e32 v61, v61, v75
	s_nop 1
	v_mov_b32_dpp v75, v61 row_half_mirror row_mask:0xf bank_mask:0xf
	s_waitcnt lgkmcnt(0)
	v_add_f32_e32 v61, v61, v75
	s_nop 1
	v_mov_b32_dpp v75, v61 row_mirror row_mask:0xf bank_mask:0xf
	s_waitcnt lgkmcnt(0)
	v_add_f32_e32 v61, v61, v75
	global_load_dword v75, v[2:3], off offset:896
	v_mov_b32_e32 v80, v61
	s_nop 1
	v_permlane16_swap_b32_e32 v80, v61
	s_waitcnt lgkmcnt(0)
; #define LAS __attribute__((address_space(3)))
; __device__ __forceinline__ bf16_t f2bf(float f) { unsigned u = __float_as_uint(f); u += 0x7FFFu + ((u >> 16) & 1u); return (bf16_t)(u >> 16); }
; __device__ __forceinline__ void df_unit(LAS unsigned char* lds, const bf16_t* qkv, bf16_t* attout, const float* subg, int b_, int h_, int qb_, int wid, int) {
;     ...
;     if (jsel == 0) {
;         bf16_t* op = attout + (size_t)(b * SEQ + q0 + 4 * hi) * DM + 1024 + h * 256 + r32; const LAS float* xr = xb + (4 * hi) * 256 + r32;
; #pragma unroll
;         for (int r = 0; r < 16; ++r) { const int rowc = (r & 3) + 8 * (r >> 2); float ss = 0.f;
; #pragma unroll
;             for (int d = 0; d < 8; ++d) { o[d][r] -= xr[rowc * 256 + d * 32]; ss += o[d][r] * o[d][r]; }
;             ss += __shfl_xor(ss, 1); ss += __shfl_xor(ss, 2); ss += __shfl_xor(ss, 4); ss += __shfl_xor(ss, 8); ss += __shfl_xor(ss, 16);
;             const float rstd = (1.0f - LAMBDA_INIT) / sqrtf(ss * (1.0f / 256.0f) + SUBLN_EPS);
; #pragma unroll
;             for (int d = 0; d < 8; ++d) op[d * 32] = f2bf(o[d][r] * rstd * subg[d * 32 + r32]);
;             op += ((r & 3) == 3 ? 5 : 1) * DM; asm volatile("" : "+v"(op) :: "memory"); } }
	v_add_f32_e32 v61, v61, v80
	v_fmamk_f32 v61, v61, 0x3b800000, v190
	v_mul_f32_e32 v80, 0x4f800000, v61
	v_cmp_gt_f32_e32 vcc, s56, v61
	s_nop 1
	v_cndmask_b32_e32 v61, v61, v80, vcc
	v_sqrt_f32_e32 v80, v61
	s_nop 0
	v_add_u32_e32 v81, -1, v80
	v_fma_f32 v90, -v81, v80, v61
	v_cmp_ge_f32_e64 s[0:1], 0, v90
	v_add_u32_e32 v90, 1, v80
	s_nop 0
	v_cndmask_b32_e64 v81, v80, v81, s[0:1]
	v_fma_f32 v80, -v90, v80, v61
	v_cmp_lt_f32_e64 s[0:1], 0, v80
	s_nop 1
	v_cndmask_b32_e64 v80, v81, v90, s[0:1]
	v_mul_f32_e32 v81, 0x37800000, v80
	v_cndmask_b32_e32 v80, v80, v81, vcc
	v_cmp_class_f32_e32 vcc, v61, v189
	s_nop 1
	v_cndmask_b32_e32 v61, v80, v61, vcc
	v_div_scale_f32 v80, s[0:1], v61, v61, s87
	v_rcp_f32_e32 v81, v80
	s_nop 0
	v_fma_f32 v90, -v80, v81, 1.0
	v_fmac_f32_e32 v81, v90, v81
	v_div_scale_f32 v90, vcc, s87, v61, s87
	v_mul_f32_e32 v91, v90, v81
	v_fma_f32 v92, -v80, v91, v90
	v_fmac_f32_e32 v91, v92, v81
	v_fma_f32 v80, -v80, v91, v90
	v_div_fmas_f32 v80, v80, v81, v91
	v_div_fixup_f32 v61, v80, v61, s87
	v_mul_f32_e32 v31, v31, v61
	s_waitcnt vmcnt(0)
	v_mul_f32_e32 v31, v64, v31
	v_bfe_u32 v64, v31, 16, 1
	v_add3_u32 v31, v31, v64, s88
	flat_store_short_d16_hi v[32:33], v31
	v_mul_f32_e32 v31, v60, v61
	v_mul_f32_e32 v17, v17, v61
	v_mul_f32_e32 v31, v47, v31
	v_bfe_u32 v47, v31, 16, 1
	v_add3_u32 v31, v31, v47, s88
	flat_store_short_d16_hi v[32:33], v31 offset:64
	v_mul_f32_e32 v31, v62, v61
	v_mul_f32_e32 v31, v65, v31
	v_bfe_u32 v47, v31, 16, 1
	v_add3_u32 v31, v31, v47, s88
	flat_store_short_d16_hi v[32:33], v31 offset:128
	v_mul_f32_e32 v31, v63, v61
	v_mul_f32_e32 v31, v76, v31
	v_bfe_u32 v47, v31, 16, 1
	v_add3_u32 v31, v31, v47, s88
	flat_store_short_d16_hi v[32:33], v31 offset:192
	v_mul_f32_e32 v31, v46, v61
	v_mul_f32_e32 v31, v77, v31
	v_bfe_u32 v46, v31, 16, 1
	v_add3_u32 v31, v31, v46, s88
	v_mul_f32_e32 v17, v17, v78
	flat_store_short_d16_hi v[32:33], v31 offset:256
	v_bfe_u32 v31, v17, 16, 1
	v_add3_u32 v17, v17, v31, s88
	flat_store_short_d16_hi v[32:33], v17 offset:320
	v_mul_f32_e32 v17, v48, v61
	v_mul_f32_e32 v17, v17, v79
	v_bfe_u32 v31, v17, 16, 1
	v_add3_u32 v17, v17, v31, s88
	flat_store_short_d16_hi v[32:33], v17 offset:384
	v_mul_f32_e32 v17, v49, v61
	v_mul_f32_e32 v17, v17, v75
	v_bfe_u32 v31, v17, 16, 1
	v_add3_u32 v17, v17, v31, s88
	flat_store_short_d16_hi v[32:33], v17 offset:448
	v_lshl_add_u64 v[32:33], v[32:33], 0, s[20:21]
	v_add_u32_e32 v17, 0x2c00, v13
	ds_read2_b32 v[46:47], v17 offset1:32
	ds_read2_b32 v[48:49], v17 offset0:64 offset1:96
	global_load_dword v64, v[2:3], off
	global_load_dword v65, v[2:3], off offset:256
	global_load_dword v76, v[2:3], off offset:384
	global_load_dword v77, v[2:3], off offset:512
	global_load_dword v78, v[2:3], off offset:640
	global_load_dword v79, v[2:3], off offset:768
	s_waitcnt lgkmcnt(0)
	v_sub_f32_e32 v31, v104, v46
	v_sub_f32_e32 v60, v103, v47
	ds_read2_b32 v[46:47], v17 offset0:128 offset1:160
	v_mul_f32_e32 v61, v60, v60
	v_sub_f32_e32 v62, v102, v48
	v_sub_f32_e32 v63, v101, v49
	ds_read2_b32 v[48:49], v17 offset0:192 offset1:224
	v_fmac_f32_e32 v61, v31, v31
	v_fmac_f32_e32 v61, v62, v62
	v_fmac_f32_e32 v61, v63, v63
	s_waitcnt lgkmcnt(0)
	v_sub_f32_e32 v46, v100, v46
	v_fmac_f32_e32 v61, v46, v46
	v_sub_f32_e32 v17, v99, v47
	v_fmac_f32_e32 v61, v17, v17
	v_sub_f32_e32 v48, v98, v48
	v_fmac_f32_e32 v61, v48, v48
	v_sub_f32_e32 v49, v89, v49
	v_fmac_f32_e32 v61, v49, v49
	s_nop 1
	v_mov_b32_dpp v75, v61 quad_perm:[1,0,3,2] row_mask:0xf bank_mask:0xf
	global_load_dword v47, v[2:3], off offset:128
	s_waitcnt lgkmcnt(0)
	v_add_f32_e32 v61, v61, v75
	s_nop 1
	v_mov_b32_dpp v75, v61 quad_perm:[2,3,0,1] row_mask:0xf bank_mask:0xf
	s_waitcnt lgkmcnt(0)
	v_add_f32_e32 v61, v61, v75
	s_nop 1
	v_mov_b32_dpp v75, v61 row_half_mirror row_mask:0xf bank_mask:0xf
	s_waitcnt lgkmcnt(0)
	v_add_f32_e32 v61, v61, v75
	s_nop 1
	v_mov_b32_dpp v75, v61 row_mirror row_mask:0xf bank_mask:0xf
	s_waitcnt lgkmcnt(0)
	v_add_f32_e32 v61, v61, v75
	global_load_dword v75, v[2:3], off offset:896
	v_mov_b32_e32 v80, v61
	s_nop 1
	v_permlane16_swap_b32_e32 v80, v61
	s_waitcnt lgkmcnt(0)
	v_add_f32_e32 v61, v61, v80
	v_fmamk_f32 v61, v61, 0x3b800000, v190
	v_mul_f32_e32 v80, 0x4f800000, v61
	v_cmp_gt_f32_e32 vcc, s56, v61
	s_nop 1
	v_cndmask_b32_e32 v61, v61, v80, vcc
	v_sqrt_f32_e32 v80, v61
	s_nop 0
	v_add_u32_e32 v81, -1, v80
	v_fma_f32 v89, -v81, v80, v61
	v_cmp_ge_f32_e64 s[0:1], 0, v89
	v_add_u32_e32 v89, 1, v80
	s_nop 0
	v_cndmask_b32_e64 v81, v80, v81, s[0:1]
	v_fma_f32 v80, -v89, v80, v61
	v_cmp_lt_f32_e64 s[0:1], 0, v80
	s_nop 1
	v_cndmask_b32_e64 v80, v81, v89, s[0:1]
	v_mul_f32_e32 v81, 0x37800000, v80
	v_cndmask_b32_e32 v80, v80, v81, vcc
	v_cmp_class_f32_e32 vcc, v61, v189
	s_nop 1
	v_cndmask_b32_e32 v61, v80, v61, vcc
	v_div_scale_f32 v80, s[0:1], v61, v61, s87
	v_rcp_f32_e32 v81, v80
	s_nop 0
	v_fma_f32 v89, -v80, v81, 1.0
	v_fmac_f32_e32 v81, v89, v81
	v_div_scale_f32 v89, vcc, s87, v61, s87
	v_mul_f32_e32 v90, v89, v81
	v_fma_f32 v91, -v80, v90, v89
	v_fmac_f32_e32 v90, v91, v81
	v_fma_f32 v80, -v80, v90, v89
	v_div_fmas_f32 v80, v80, v81, v90
	v_div_fixup_f32 v61, v80, v61, s87
	v_mul_f32_e32 v31, v31, v61
	s_waitcnt vmcnt(0)
; #define LAS __attribute__((address_space(3)))
; __device__ __forceinline__ bf16_t f2bf(float f) { unsigned u = __float_as_uint(f); u += 0x7FFFu + ((u >> 16) & 1u); return (bf16_t)(u >> 16); }
; __device__ __forceinline__ void df_unit(LAS unsigned char* lds, const bf16_t* qkv, bf16_t* attout, const float* subg, int b_, int h_, int qb_, int wid, int) {
;     ...
;     if (jsel == 0) {
;         bf16_t* op = attout + (size_t)(b * SEQ + q0 + 4 * hi) * DM + 1024 + h * 256 + r32; const LAS float* xr = xb + (4 * hi) * 256 + r32;
; #pragma unroll
;         for (int r = 0; r < 16; ++r) { const int rowc = (r & 3) + 8 * (r >> 2); float ss = 0.f;
; #pragma unroll
;             for (int d = 0; d < 8; ++d) { o[d][r] -= xr[rowc * 256 + d * 32]; ss += o[d][r] * o[d][r]; }
;             ss += __shfl_xor(ss, 1); ss += __shfl_xor(ss, 2); ss += __shfl_xor(ss, 4); ss += __shfl_xor(ss, 8); ss += __shfl_xor(ss, 16);
;             const float rstd = (1.0f - LAMBDA_INIT) / sqrtf(ss * (1.0f / 256.0f) + SUBLN_EPS);
; #pragma unroll
;             for (int d = 0; d < 8; ++d) op[d * 32] = f2bf(o[d][r] * rstd * subg[d * 32 + r32]);
;             op += ((r & 3) == 3 ? 5 : 1) * DM; asm volatile("" : "+v"(op) :: "memory"); } }
	v_mul_f32_e32 v31, v64, v31
	v_bfe_u32 v64, v31, 16, 1
	v_add3_u32 v31, v31, v64, s88
	flat_store_short_d16_hi v[32:33], v31
	v_mul_f32_e32 v31, v60, v61
	v_mul_f32_e32 v17, v17, v61
	v_mul_f32_e32 v31, v47, v31
	v_bfe_u32 v47, v31, 16, 1
	v_add3_u32 v31, v31, v47, s88
	flat_store_short_d16_hi v[32:33], v31 offset:64
	v_mul_f32_e32 v31, v62, v61
	v_mul_f32_e32 v31, v65, v31
	v_bfe_u32 v47, v31, 16, 1
	v_add3_u32 v31, v31, v47, s88
	flat_store_short_d16_hi v[32:33], v31 offset:128
	v_mul_f32_e32 v31, v63, v61
	v_mul_f32_e32 v31, v76, v31
	v_bfe_u32 v47, v31, 16, 1
	v_add3_u32 v31, v31, v47, s88
	flat_store_short_d16_hi v[32:33], v31 offset:192
	v_mul_f32_e32 v31, v46, v61
	v_mul_f32_e32 v31, v77, v31
	v_bfe_u32 v46, v31, 16, 1
	v_add3_u32 v31, v31, v46, s88
	v_mul_f32_e32 v17, v17, v78
	flat_store_short_d16_hi v[32:33], v31 offset:256
	v_bfe_u32 v31, v17, 16, 1
	v_add3_u32 v17, v17, v31, s88
	flat_store_short_d16_hi v[32:33], v17 offset:320
	v_mul_f32_e32 v17, v48, v61
	v_mul_f32_e32 v17, v17, v79
	v_bfe_u32 v31, v17, 16, 1
	v_add3_u32 v17, v17, v31, s88
	flat_store_short_d16_hi v[32:33], v17 offset:384
	v_mul_f32_e32 v17, v49, v61
	v_mul_f32_e32 v17, v17, v75
	v_bfe_u32 v31, v17, 16, 1
	v_add3_u32 v17, v17, v31, s88
	flat_store_short_d16_hi v[32:33], v17 offset:448
	v_lshl_add_u64 v[32:33], v[32:33], 0, s[22:23]
	v_add_u32_e32 v17, 0x4000, v13
	ds_read2_b32 v[46:47], v17 offset1:32
	ds_read2_b32 v[48:49], v17 offset0:64 offset1:96
	global_load_dword v64, v[2:3], off
	global_load_dword v65, v[2:3], off offset:256
	global_load_dword v75, v[2:3], off offset:384
	global_load_dword v76, v[2:3], off offset:512
	global_load_dword v77, v[2:3], off offset:640
	global_load_dword v78, v[2:3], off offset:768
	s_waitcnt lgkmcnt(0)
	v_sub_f32_e32 v31, v88, v46
	v_sub_f32_e32 v60, v87, v47
	ds_read2_b32 v[46:47], v17 offset0:128 offset1:160
	v_mul_f32_e32 v61, v60, v60
	v_sub_f32_e32 v62, v86, v48
	v_sub_f32_e32 v63, v85, v49
	ds_read2_b32 v[48:49], v17 offset0:192 offset1:224
	v_fmac_f32_e32 v61, v31, v31
	v_fmac_f32_e32 v61, v62, v62
	v_fmac_f32_e32 v61, v63, v63
	s_waitcnt lgkmcnt(0)
	v_sub_f32_e32 v46, v84, v46
	v_fmac_f32_e32 v61, v46, v46
	v_sub_f32_e32 v17, v83, v47
	v_fmac_f32_e32 v61, v17, v17
	v_sub_f32_e32 v48, v82, v48
	v_fmac_f32_e32 v61, v48, v48
	v_sub_f32_e32 v49, v74, v49
	v_fmac_f32_e32 v61, v49, v49
	s_nop 1
	v_mov_b32_dpp v74, v61 quad_perm:[1,0,3,2] row_mask:0xf bank_mask:0xf
	global_load_dword v47, v[2:3], off offset:128
	s_waitcnt lgkmcnt(0)
	v_add_f32_e32 v61, v61, v74
	s_nop 1
	v_mov_b32_dpp v74, v61 quad_perm:[2,3,0,1] row_mask:0xf bank_mask:0xf
	s_waitcnt lgkmcnt(0)
	v_add_f32_e32 v61, v61, v74
	s_nop 1
	v_mov_b32_dpp v74, v61 row_half_mirror row_mask:0xf bank_mask:0xf
	s_waitcnt lgkmcnt(0)
	v_add_f32_e32 v61, v61, v74
	s_nop 1
	v_mov_b32_dpp v74, v61 row_mirror row_mask:0xf bank_mask:0xf
	s_waitcnt lgkmcnt(0)
	v_add_f32_e32 v61, v61, v74
	global_load_dword v74, v[2:3], off offset:896
	v_mov_b32_e32 v79, v61
	s_nop 1
	v_permlane16_swap_b32_e32 v79, v61
	s_waitcnt lgkmcnt(0)
	v_add_f32_e32 v61, v61, v79
	v_fmamk_f32 v61, v61, 0x3b800000, v190
	v_mul_f32_e32 v79, 0x4f800000, v61
	v_cmp_gt_f32_e32 vcc, s56, v61
	s_nop 1
	v_cndmask_b32_e32 v61, v61, v79, vcc
	v_sqrt_f32_e32 v79, v61
	s_nop 0
	v_add_u32_e32 v80, -1, v79
	v_fma_f32 v81, -v80, v79, v61
	v_cmp_ge_f32_e64 s[0:1], 0, v81
	v_add_u32_e32 v81, 1, v79
	s_nop 0
	v_cndmask_b32_e64 v80, v79, v80, s[0:1]
	v_fma_f32 v79, -v81, v79, v61
	v_cmp_lt_f32_e64 s[0:1], 0, v79
	s_nop 1
	v_cndmask_b32_e64 v79, v80, v81, s[0:1]
	v_mul_f32_e32 v80, 0x37800000, v79
	v_cndmask_b32_e32 v79, v79, v80, vcc
	v_cmp_class_f32_e32 vcc, v61, v189
	s_nop 1
	v_cndmask_b32_e32 v61, v79, v61, vcc
	v_div_scale_f32 v79, s[0:1], v61, v61, s87
	v_rcp_f32_e32 v80, v79
	s_nop 0
	v_fma_f32 v81, -v79, v80, 1.0
	v_fmac_f32_e32 v80, v81, v80
	v_div_scale_f32 v81, vcc, s87, v61, s87
	v_mul_f32_e32 v82, v81, v80
	v_fma_f32 v83, -v79, v82, v81
	v_fmac_f32_e32 v82, v83, v80
	v_fma_f32 v79, -v79, v82, v81
	v_div_fmas_f32 v79, v79, v80, v82
	v_div_fixup_f32 v61, v79, v61, s87
	v_mul_f32_e32 v31, v31, v61
	s_waitcnt vmcnt(0)
	v_mul_f32_e32 v31, v64, v31
	v_bfe_u32 v64, v31, 16, 1
	v_add3_u32 v31, v31, v64, s88
	flat_store_short_d16_hi v[32:33], v31
	v_mul_f32_e32 v31, v60, v61
	v_mul_f32_e32 v17, v17, v61
	v_mul_f32_e32 v31, v47, v31
	v_bfe_u32 v47, v31, 16, 1
	v_add3_u32 v31, v31, v47, s88
	flat_store_short_d16_hi v[32:33], v31 offset:64
	v_mul_f32_e32 v31, v62, v61
	v_mul_f32_e32 v31, v65, v31
	v_bfe_u32 v47, v31, 16, 1
	v_add3_u32 v31, v31, v47, s88
	flat_store_short_d16_hi v[32:33], v31 offset:128
	v_mul_f32_e32 v31, v63, v61
	v_mul_f32_e32 v31, v75, v31
	v_bfe_u32 v47, v31, 16, 1
	v_add3_u32 v31, v31, v47, s88
	flat_store_short_d16_hi v[32:33], v31 offset:192
	v_mul_f32_e32 v31, v46, v61
	v_mul_f32_e32 v31, v76, v31
	v_bfe_u32 v46, v31, 16, 1
	v_add3_u32 v31, v31, v46, s88
	v_mul_f32_e32 v17, v17, v77
	flat_store_short_d16_hi v[32:33], v31 offset:256
	v_bfe_u32 v31, v17, 16, 1
	v_add3_u32 v17, v17, v31, s88
	flat_store_short_d16_hi v[32:33], v17 offset:320
	v_mul_f32_e32 v17, v48, v61
	v_mul_f32_e32 v17, v17, v78
	v_bfe_u32 v31, v17, 16, 1
	v_add3_u32 v17, v17, v31, s88
	flat_store_short_d16_hi v[32:33], v17 offset:384
	v_mul_f32_e32 v17, v49, v61
	v_mul_f32_e32 v17, v17, v74
	v_bfe_u32 v31, v17, 16, 1
	v_add3_u32 v17, v17, v31, s88
	flat_store_short_d16_hi v[32:33], v17 offset:448
	v_lshl_add_u64 v[32:33], v[32:33], 0, s[20:21]
	v_add_u32_e32 v17, 0x4400, v13
	ds_read2_b32 v[46:47], v17 offset1:32
	ds_read2_b32 v[48:49], v17 offset0:64 offset1:96
	global_load_dword v64, v[2:3], off
	global_load_dword v65, v[2:3], off offset:256
	s_waitcnt lgkmcnt(0)
; #define LAS __attribute__((address_space(3)))
; __device__ __forceinline__ bf16_t f2bf(float f) { unsigned u = __float_as_uint(f); u += 0x7FFFu + ((u >> 16) & 1u); return (bf16_t)(u >> 16); }
; __device__ __forceinline__ void df_unit(LAS unsigned char* lds, const bf16_t* qkv, bf16_t* attout, const float* subg, int b_, int h_, int qb_, int wid, int) {
;     ...
;     if (jsel == 0) {
;         bf16_t* op = attout + (size_t)(b * SEQ + q0 + 4 * hi) * DM + 1024 + h * 256 + r32; const LAS float* xr = xb + (4 * hi) * 256 + r32;
; #pragma unroll
;         for (int r = 0; r < 16; ++r) { const int rowc = (r & 3) + 8 * (r >> 2); float ss = 0.f;
; #pragma unroll
;             for (int d = 0; d < 8; ++d) { o[d][r] -= xr[rowc * 256 + d * 32]; ss += o[d][r] * o[d][r]; }
;             ss += __shfl_xor(ss, 1); ss += __shfl_xor(ss, 2); ss += __shfl_xor(ss, 4); ss += __shfl_xor(ss, 8); ss += __shfl_xor(ss, 16);
;             const float rstd = (1.0f - LAMBDA_INIT) / sqrtf(ss * (1.0f / 256.0f) + SUBLN_EPS);
; #pragma unroll
;             for (int d = 0; d < 8; ++d) op[d * 32] = f2bf(o[d][r] * rstd * subg[d * 32 + r32]);
;             op += ((r & 3) == 3 ? 5 : 1) * DM; asm volatile("" : "+v"(op) :: "memory"); } }
	v_sub_f32_e32 v31, v73, v46
	v_sub_f32_e32 v60, v72, v47
	ds_read2_b32 v[46:47], v17 offset0:128 offset1:160
	v_mul_f32_e32 v61, v60, v60
	v_sub_f32_e32 v62, v71, v48
	v_sub_f32_e32 v63, v70, v49
	ds_read2_b32 v[48:49], v17 offset0:192 offset1:224
	v_fmac_f32_e32 v61, v31, v31
	v_fmac_f32_e32 v61, v62, v62
	v_fmac_f32_e32 v61, v63, v63
	s_waitcnt lgkmcnt(0)
	v_sub_f32_e32 v46, v69, v46
	v_fmac_f32_e32 v61, v46, v46
	v_sub_f32_e32 v17, v68, v47
	v_fmac_f32_e32 v61, v17, v17
	v_sub_f32_e32 v48, v67, v48
	v_fmac_f32_e32 v61, v48, v48
	v_sub_f32_e32 v49, v66, v49
	v_fmac_f32_e32 v61, v49, v49
	s_nop 1
	v_mov_b32_dpp v66, v61 quad_perm:[1,0,3,2] row_mask:0xf bank_mask:0xf
	global_load_dword v47, v[2:3], off offset:128
	global_load_dword v67, v[2:3], off offset:384
	global_load_dword v68, v[2:3], off offset:512
	global_load_dword v69, v[2:3], off offset:640
	global_load_dword v70, v[2:3], off offset:768
	s_waitcnt lgkmcnt(0)
	v_add_f32_e32 v61, v61, v66
	s_nop 1
	v_mov_b32_dpp v66, v61 quad_perm:[2,3,0,1] row_mask:0xf bank_mask:0xf
	s_waitcnt lgkmcnt(0)
	v_add_f32_e32 v61, v61, v66
	s_nop 1
	v_mov_b32_dpp v66, v61 row_half_mirror row_mask:0xf bank_mask:0xf
	s_waitcnt lgkmcnt(0)
	v_add_f32_e32 v61, v61, v66
	s_nop 1
	v_mov_b32_dpp v66, v61 row_mirror row_mask:0xf bank_mask:0xf
	s_waitcnt lgkmcnt(0)
	v_add_f32_e32 v61, v61, v66
	global_load_dword v66, v[2:3], off offset:896
	v_mov_b32_e32 v71, v61
	s_nop 1
	v_permlane16_swap_b32_e32 v71, v61
	s_waitcnt lgkmcnt(0)
	v_add_f32_e32 v61, v61, v71
	v_fmamk_f32 v61, v61, 0x3b800000, v190
	v_mul_f32_e32 v71, 0x4f800000, v61
	v_cmp_gt_f32_e32 vcc, s56, v61
	s_nop 1
	v_cndmask_b32_e32 v61, v61, v71, vcc
	v_sqrt_f32_e32 v71, v61
	s_nop 0
	v_add_u32_e32 v72, -1, v71
	v_fma_f32 v73, -v72, v71, v61
	v_cmp_ge_f32_e64 s[0:1], 0, v73
	v_add_u32_e32 v73, 1, v71
	s_nop 0
	v_cndmask_b32_e64 v72, v71, v72, s[0:1]
	v_fma_f32 v71, -v73, v71, v61
	v_cmp_lt_f32_e64 s[0:1], 0, v71
	s_nop 1
	v_cndmask_b32_e64 v71, v72, v73, s[0:1]
	v_mul_f32_e32 v72, 0x37800000, v71
	v_cndmask_b32_e32 v71, v71, v72, vcc
	v_cmp_class_f32_e32 vcc, v61, v189
	s_nop 1
	v_cndmask_b32_e32 v61, v71, v61, vcc
	v_div_scale_f32 v71, s[0:1], v61, v61, s87
	v_rcp_f32_e32 v72, v71
	s_nop 0
	v_fma_f32 v73, -v71, v72, 1.0
	v_fmac_f32_e32 v72, v73, v72
	v_div_scale_f32 v73, vcc, s87, v61, s87
	v_mul_f32_e32 v74, v73, v72
	v_fma_f32 v75, -v71, v74, v73
	v_fmac_f32_e32 v74, v75, v72
	v_fma_f32 v71, -v71, v74, v73
	v_div_fmas_f32 v71, v71, v72, v74
	v_div_fixup_f32 v61, v71, v61, s87
	v_mul_f32_e32 v31, v31, v61
	s_waitcnt vmcnt(0)
	v_mul_f32_e32 v31, v64, v31
	v_bfe_u32 v64, v31, 16, 1
	v_add3_u32 v31, v31, v64, s88
	flat_store_short_d16_hi v[32:33], v31
	v_mul_f32_e32 v31, v60, v61
	v_mul_f32_e32 v31, v47, v31
	v_bfe_u32 v47, v31, 16, 1
	v_add3_u32 v31, v31, v47, s88
	flat_store_short_d16_hi v[32:33], v31 offset:64
	v_mul_f32_e32 v31, v62, v61
	v_mul_f32_e32 v31, v65, v31
	v_bfe_u32 v47, v31, 16, 1
	v_add3_u32 v31, v31, v47, s88
	flat_store_short_d16_hi v[32:33], v31 offset:128
	v_mul_f32_e32 v31, v63, v61
	v_mul_f32_e32 v31, v67, v31
	v_bfe_u32 v47, v31, 16, 1
	v_add3_u32 v31, v31, v47, s88
	flat_store_short_d16_hi v[32:33], v31 offset:192
	v_mul_f32_e32 v31, v46, v61
	v_mul_f32_e32 v31, v68, v31
	v_bfe_u32 v46, v31, 16, 1
	v_mul_f32_e32 v17, v17, v61
	v_add3_u32 v31, v31, v46, s88
	v_mul_f32_e32 v17, v17, v69
	flat_store_short_d16_hi v[32:33], v31 offset:256
	v_bfe_u32 v31, v17, 16, 1
	v_add3_u32 v17, v17, v31, s88
	flat_store_short_d16_hi v[32:33], v17 offset:320
	v_mul_f32_e32 v17, v48, v61
	v_mul_f32_e32 v17, v17, v70
	v_bfe_u32 v31, v17, 16, 1
	v_add3_u32 v17, v17, v31, s88
	flat_store_short_d16_hi v[32:33], v17 offset:384
	v_mul_f32_e32 v17, v49, v61
	v_mul_f32_e32 v17, v17, v66
	v_bfe_u32 v31, v17, 16, 1
	v_add3_u32 v17, v17, v31, s88
	flat_store_short_d16_hi v[32:33], v17 offset:448
	v_lshl_add_u64 v[32:33], v[32:33], 0, s[20:21]
	v_add_u32_e32 v17, 0x4800, v13
	ds_read2_b32 v[46:47], v17 offset1:32
	ds_read2_b32 v[48:49], v17 offset0:64 offset1:96
	global_load_dword v60, v[2:3], off offset:512
	global_load_dword v61, v[2:3], off offset:640
	global_load_dword v62, v[2:3], off offset:768
	s_waitcnt lgkmcnt(0)
	v_sub_f32_e32 v31, v59, v46
	v_sub_f32_e32 v58, v58, v47
	ds_read2_b32 v[46:47], v17 offset0:128 offset1:160
	v_mul_f32_e32 v59, v58, v58
	v_sub_f32_e32 v57, v57, v48
	v_sub_f32_e32 v56, v56, v49
	ds_read2_b32 v[48:49], v17 offset0:192 offset1:224
	v_fmac_f32_e32 v59, v31, v31
	v_fmac_f32_e32 v59, v57, v57
	v_fmac_f32_e32 v59, v56, v56
	s_waitcnt lgkmcnt(0)
	v_sub_f32_e32 v46, v55, v46
	v_fmac_f32_e32 v59, v46, v46
	v_sub_f32_e32 v17, v54, v47
	global_load_dword v55, v[2:3], off
	global_load_dword v47, v[2:3], off offset:128
	global_load_dword v54, v[2:3], off offset:384
	v_fmac_f32_e32 v59, v17, v17
	v_sub_f32_e32 v48, v53, v48
	v_fmac_f32_e32 v59, v48, v48
	v_sub_f32_e32 v49, v52, v49
	v_fmac_f32_e32 v59, v49, v49
	s_nop 1
	v_mov_b32_dpp v53, v59 quad_perm:[1,0,3,2] row_mask:0xf bank_mask:0xf
	global_load_dword v52, v[2:3], off offset:256
	s_waitcnt lgkmcnt(0)
	v_add_f32_e32 v53, v59, v53
	s_nop 1
	v_mov_b32_dpp v59, v53 quad_perm:[2,3,0,1] row_mask:0xf bank_mask:0xf
	s_waitcnt lgkmcnt(0)
	v_add_f32_e32 v53, v53, v59
	s_nop 1
	v_mov_b32_dpp v59, v53 row_half_mirror row_mask:0xf bank_mask:0xf
	s_waitcnt lgkmcnt(0)
	v_add_f32_e32 v53, v53, v59
	s_nop 1
	v_mov_b32_dpp v59, v53 row_mirror row_mask:0xf bank_mask:0xf
	s_waitcnt lgkmcnt(0)
	v_add_f32_e32 v53, v53, v59
	global_load_dword v59, v[2:3], off offset:896
	v_mov_b32_e32 v63, v53
	s_nop 1
	v_permlane16_swap_b32_e32 v63, v53
	s_waitcnt lgkmcnt(0)
; #define LAS __attribute__((address_space(3)))
; __device__ __forceinline__ bf16_t f2bf(float f) { unsigned u = __float_as_uint(f); u += 0x7FFFu + ((u >> 16) & 1u); return (bf16_t)(u >> 16); }
; __device__ __forceinline__ void df_unit(LAS unsigned char* lds, const bf16_t* qkv, bf16_t* attout, const float* subg, int b_, int h_, int qb_, int wid, int) {
;     ...
;     if (jsel == 0) {
;         bf16_t* op = attout + (size_t)(b * SEQ + q0 + 4 * hi) * DM + 1024 + h * 256 + r32; const LAS float* xr = xb + (4 * hi) * 256 + r32;
; #pragma unroll
;         for (int r = 0; r < 16; ++r) { const int rowc = (r & 3) + 8 * (r >> 2); float ss = 0.f;
; #pragma unroll
;             for (int d = 0; d < 8; ++d) { o[d][r] -= xr[rowc * 256 + d * 32]; ss += o[d][r] * o[d][r]; }
;             ss += __shfl_xor(ss, 1); ss += __shfl_xor(ss, 2); ss += __shfl_xor(ss, 4); ss += __shfl_xor(ss, 8); ss += __shfl_xor(ss, 16);
;             const float rstd = (1.0f - LAMBDA_INIT) / sqrtf(ss * (1.0f / 256.0f) + SUBLN_EPS);
; #pragma unroll
;             for (int d = 0; d < 8; ++d) op[d * 32] = f2bf(o[d][r] * rstd * subg[d * 32 + r32]);
;             op += ((r & 3) == 3 ? 5 : 1) * DM; asm volatile("" : "+v"(op) :: "memory"); } }
	v_add_f32_e32 v53, v53, v63
	v_fmamk_f32 v53, v53, 0x3b800000, v190
	v_mul_f32_e32 v63, 0x4f800000, v53
	v_cmp_gt_f32_e32 vcc, s56, v53
	s_nop 1
	v_cndmask_b32_e32 v53, v53, v63, vcc
	v_sqrt_f32_e32 v63, v53
	s_nop 0
	v_add_u32_e32 v64, -1, v63
	v_fma_f32 v65, -v64, v63, v53
	v_cmp_ge_f32_e64 s[0:1], 0, v65
	v_add_u32_e32 v65, 1, v63
	s_nop 0
	v_cndmask_b32_e64 v64, v63, v64, s[0:1]
	v_fma_f32 v63, -v65, v63, v53
	v_cmp_lt_f32_e64 s[0:1], 0, v63
	s_nop 1
	v_cndmask_b32_e64 v63, v64, v65, s[0:1]
	v_mul_f32_e32 v64, 0x37800000, v63
	v_cndmask_b32_e32 v63, v63, v64, vcc
	v_cmp_class_f32_e32 vcc, v53, v189
	s_nop 1
	v_cndmask_b32_e32 v53, v63, v53, vcc
	v_div_scale_f32 v63, s[0:1], v53, v53, s87
	v_rcp_f32_e32 v64, v63
	s_nop 0
	v_fma_f32 v65, -v63, v64, 1.0
	v_fmac_f32_e32 v64, v65, v64
	v_div_scale_f32 v65, vcc, s87, v53, s87
	v_mul_f32_e32 v66, v65, v64
	v_fma_f32 v67, -v63, v66, v65
	v_fmac_f32_e32 v66, v67, v64
	v_fma_f32 v63, -v63, v66, v65
	v_div_fmas_f32 v63, v63, v64, v66
	v_div_fixup_f32 v53, v63, v53, s87
	v_mul_f32_e32 v31, v31, v53
	s_waitcnt vmcnt(0)
	v_mul_f32_e32 v31, v55, v31
	v_bfe_u32 v55, v31, 16, 1
	v_add3_u32 v31, v31, v55, s88
	flat_store_short_d16_hi v[32:33], v31
	v_mul_f32_e32 v31, v58, v53
	v_mul_f32_e32 v31, v47, v31
	v_bfe_u32 v47, v31, 16, 1
	v_add3_u32 v31, v31, v47, s88
	flat_store_short_d16_hi v[32:33], v31 offset:64
	v_mul_f32_e32 v31, v57, v53
	v_mul_f32_e32 v31, v52, v31
	v_bfe_u32 v47, v31, 16, 1
	v_add3_u32 v31, v31, v47, s88
	flat_store_short_d16_hi v[32:33], v31 offset:128
	v_mul_f32_e32 v31, v56, v53
	v_mul_f32_e32 v31, v54, v31
	v_bfe_u32 v47, v31, 16, 1
	v_add3_u32 v31, v31, v47, s88
	flat_store_short_d16_hi v[32:33], v31 offset:192
	v_mul_f32_e32 v31, v46, v53
	v_mul_f32_e32 v31, v60, v31
	v_bfe_u32 v46, v31, 16, 1
	v_mul_f32_e32 v17, v17, v53
	v_add3_u32 v31, v31, v46, s88
	v_mul_f32_e32 v17, v17, v61
	flat_store_short_d16_hi v[32:33], v31 offset:256
	v_bfe_u32 v31, v17, 16, 1
	v_add3_u32 v17, v17, v31, s88
	flat_store_short_d16_hi v[32:33], v17 offset:320
	v_mul_f32_e32 v17, v48, v53
	v_mul_f32_e32 v17, v17, v62
	v_bfe_u32 v31, v17, 16, 1
	v_add3_u32 v17, v17, v31, s88
	flat_store_short_d16_hi v[32:33], v17 offset:384
	v_mul_f32_e32 v17, v49, v53
	v_mul_f32_e32 v17, v17, v59
	v_bfe_u32 v31, v17, 16, 1
	v_add3_u32 v17, v17, v31, s88
	flat_store_short_d16_hi v[32:33], v17 offset:448
	v_lshl_add_u64 v[32:33], v[32:33], 0, s[20:21]
	v_add_u32_e32 v17, 0x4c00, v13
	ds_read2_b32 v[46:47], v17 offset1:32
	ds_read2_b32 v[48:49], v17 offset0:64 offset1:96
	global_load_dword v52, v[2:3], off offset:512
	global_load_dword v53, v[2:3], off offset:640
	global_load_dword v54, v[2:3], off offset:768
	s_waitcnt lgkmcnt(0)
	v_sub_f32_e32 v31, v51, v46
	v_sub_f32_e32 v50, v50, v47
	ds_read2_b32 v[46:47], v17 offset0:128 offset1:160
	v_mul_f32_e32 v51, v50, v50
	v_sub_f32_e32 v48, v45, v48
	v_sub_f32_e32 v49, v44, v49
	ds_read2_b32 v[44:45], v17 offset0:192 offset1:224
	v_fmac_f32_e32 v51, v31, v31
	v_fmac_f32_e32 v51, v48, v48
	v_fmac_f32_e32 v51, v49, v49
	s_waitcnt lgkmcnt(0)
	v_sub_f32_e32 v43, v43, v46
	v_fmac_f32_e32 v51, v43, v43
	v_sub_f32_e32 v17, v42, v47
	global_load_dword v46, v[2:3], off
	global_load_dword v42, v[2:3], off offset:128
	global_load_dword v47, v[2:3], off offset:384
	v_fmac_f32_e32 v51, v17, v17
	v_sub_f32_e32 v41, v41, v44
	v_fmac_f32_e32 v51, v41, v41
	v_sub_f32_e32 v40, v40, v45
	v_fmac_f32_e32 v51, v40, v40
	s_nop 1
	v_mov_b32_dpp v45, v51 quad_perm:[1,0,3,2] row_mask:0xf bank_mask:0xf
	global_load_dword v44, v[2:3], off offset:256
	s_waitcnt lgkmcnt(0)
	v_add_f32_e32 v45, v51, v45
	s_nop 1
	v_mov_b32_dpp v51, v45 quad_perm:[2,3,0,1] row_mask:0xf bank_mask:0xf
	s_waitcnt lgkmcnt(0)
	v_add_f32_e32 v45, v45, v51
	s_nop 1
	v_mov_b32_dpp v51, v45 row_half_mirror row_mask:0xf bank_mask:0xf
	s_waitcnt lgkmcnt(0)
	v_add_f32_e32 v45, v45, v51
	s_nop 1
	v_mov_b32_dpp v51, v45 row_mirror row_mask:0xf bank_mask:0xf
	s_waitcnt lgkmcnt(0)
	v_add_f32_e32 v45, v45, v51
	global_load_dword v51, v[2:3], off offset:896
	v_mov_b32_e32 v55, v45
	s_nop 1
	v_permlane16_swap_b32_e32 v55, v45
	s_waitcnt lgkmcnt(0)
	v_add_f32_e32 v45, v45, v55
	v_fmamk_f32 v45, v45, 0x3b800000, v190
	v_mul_f32_e32 v55, 0x4f800000, v45
	v_cmp_gt_f32_e32 vcc, s56, v45
	s_nop 1
	v_cndmask_b32_e32 v45, v45, v55, vcc
	v_sqrt_f32_e32 v55, v45
	s_nop 0
	v_add_u32_e32 v56, -1, v55
	v_fma_f32 v57, -v56, v55, v45
	v_cmp_ge_f32_e64 s[0:1], 0, v57
	v_add_u32_e32 v57, 1, v55
	s_nop 0
	v_cndmask_b32_e64 v56, v55, v56, s[0:1]
	v_fma_f32 v55, -v57, v55, v45
	v_cmp_lt_f32_e64 s[0:1], 0, v55
	s_nop 1
	v_cndmask_b32_e64 v55, v56, v57, s[0:1]
	v_mul_f32_e32 v56, 0x37800000, v55
	v_cndmask_b32_e32 v55, v55, v56, vcc
	v_cmp_class_f32_e32 vcc, v45, v189
	s_nop 1
	v_cndmask_b32_e32 v45, v55, v45, vcc
	v_div_scale_f32 v55, s[0:1], v45, v45, s87
	v_rcp_f32_e32 v56, v55
	s_nop 0
	v_fma_f32 v57, -v55, v56, 1.0
	v_fmac_f32_e32 v56, v57, v56
	v_div_scale_f32 v57, vcc, s87, v45, s87
	v_mul_f32_e32 v58, v57, v56
	v_fma_f32 v59, -v55, v58, v57
	v_fmac_f32_e32 v58, v59, v56
	v_fma_f32 v55, -v55, v58, v57
	v_div_fmas_f32 v55, v55, v56, v58
	v_div_fixup_f32 v45, v55, v45, s87
	v_mul_f32_e32 v31, v31, v45
	s_waitcnt vmcnt(0)
; #define LAS __attribute__((address_space(3)))
; __device__ __forceinline__ bf16_t f2bf(float f) { unsigned u = __float_as_uint(f); u += 0x7FFFu + ((u >> 16) & 1u); return (bf16_t)(u >> 16); }
; __device__ __forceinline__ void df_unit(LAS unsigned char* lds, const bf16_t* qkv, bf16_t* attout, const float* subg, int b_, int h_, int qb_, int wid, int) {
;     ...
;     if (jsel == 0) {
;         bf16_t* op = attout + (size_t)(b * SEQ + q0 + 4 * hi) * DM + 1024 + h * 256 + r32; const LAS float* xr = xb + (4 * hi) * 256 + r32;
; #pragma unroll
;         for (int r = 0; r < 16; ++r) { const int rowc = (r & 3) + 8 * (r >> 2); float ss = 0.f;
; #pragma unroll
;             for (int d = 0; d < 8; ++d) { o[d][r] -= xr[rowc * 256 + d * 32]; ss += o[d][r] * o[d][r]; }
;             ss += __shfl_xor(ss, 1); ss += __shfl_xor(ss, 2); ss += __shfl_xor(ss, 4); ss += __shfl_xor(ss, 8); ss += __shfl_xor(ss, 16);
;             const float rstd = (1.0f - LAMBDA_INIT) / sqrtf(ss * (1.0f / 256.0f) + SUBLN_EPS);
; #pragma unroll
;             for (int d = 0; d < 8; ++d) op[d * 32] = f2bf(o[d][r] * rstd * subg[d * 32 + r32]);
;             op += ((r & 3) == 3 ? 5 : 1) * DM; asm volatile("" : "+v"(op) :: "memory"); } }
	v_mul_f32_e32 v31, v46, v31
	v_bfe_u32 v46, v31, 16, 1
	v_add3_u32 v31, v31, v46, s88
	flat_store_short_d16_hi v[32:33], v31
	v_mul_f32_e32 v31, v50, v45
	v_mul_f32_e32 v31, v42, v31
	v_bfe_u32 v42, v31, 16, 1
	v_add3_u32 v31, v31, v42, s88
	flat_store_short_d16_hi v[32:33], v31 offset:64
	v_mul_f32_e32 v31, v48, v45
	v_mul_f32_e32 v31, v44, v31
	v_bfe_u32 v42, v31, 16, 1
	v_add3_u32 v31, v31, v42, s88
	flat_store_short_d16_hi v[32:33], v31 offset:128
	v_mul_f32_e32 v31, v49, v45
	v_mul_f32_e32 v31, v47, v31
	v_bfe_u32 v42, v31, 16, 1
	v_add3_u32 v31, v31, v42, s88
	flat_store_short_d16_hi v[32:33], v31 offset:192
	v_mul_f32_e32 v31, v43, v45
	v_mul_f32_e32 v31, v52, v31
	v_bfe_u32 v42, v31, 16, 1
	v_mul_f32_e32 v17, v17, v45
	v_add3_u32 v31, v31, v42, s88
	v_mul_f32_e32 v17, v17, v53
	flat_store_short_d16_hi v[32:33], v31 offset:256
	v_bfe_u32 v31, v17, 16, 1
	v_add3_u32 v17, v17, v31, s88
	flat_store_short_d16_hi v[32:33], v17 offset:320
	v_mul_f32_e32 v17, v41, v45
	v_mul_f32_e32 v17, v17, v54
	v_bfe_u32 v31, v17, 16, 1
	v_add3_u32 v17, v17, v31, s88
	flat_store_short_d16_hi v[32:33], v17 offset:384
	v_mul_f32_e32 v17, v40, v45
	v_mul_f32_e32 v17, v17, v51
	v_bfe_u32 v31, v17, 16, 1
	v_add3_u32 v17, v17, v31, s88
	flat_store_short_d16_hi v[32:33], v17 offset:448
	v_lshl_add_u64 v[32:33], v[32:33], 0, s[22:23]
	v_add_u32_e32 v17, 0x6000, v13
	ds_read2_b32 v[40:41], v17 offset1:32
	ds_read2_b32 v[42:43], v17 offset0:64 offset1:96
	global_load_dword v44, v[2:3], off offset:512
	global_load_dword v45, v[2:3], off offset:640
	global_load_dword v46, v[2:3], off offset:768
	s_waitcnt lgkmcnt(0)
	v_sub_f32_e32 v31, v39, v40
	v_sub_f32_e32 v40, v38, v41
	ds_read2_b32 v[38:39], v17 offset0:128 offset1:160
	v_mul_f32_e32 v41, v40, v40
	v_sub_f32_e32 v42, v37, v42
	v_sub_f32_e32 v43, v36, v43
	ds_read2_b32 v[36:37], v17 offset0:192 offset1:224
	v_fmac_f32_e32 v41, v31, v31
	v_fmac_f32_e32 v41, v42, v42
	v_fmac_f32_e32 v41, v43, v43
	s_waitcnt lgkmcnt(0)
	v_sub_f32_e32 v35, v35, v38
	v_fmac_f32_e32 v41, v35, v35
	v_sub_f32_e32 v17, v34, v39
	global_load_dword v38, v[2:3], off
	global_load_dword v34, v[2:3], off offset:128
	global_load_dword v39, v[2:3], off offset:384
	v_fmac_f32_e32 v41, v17, v17
	v_sub_f32_e32 v30, v30, v36
	v_fmac_f32_e32 v41, v30, v30
	v_sub_f32_e32 v29, v29, v37
	v_fmac_f32_e32 v41, v29, v29
	s_nop 1
	v_mov_b32_dpp v37, v41 quad_perm:[1,0,3,2] row_mask:0xf bank_mask:0xf
	global_load_dword v36, v[2:3], off offset:256
	s_waitcnt lgkmcnt(0)
	v_add_f32_e32 v37, v41, v37
	s_nop 1
	v_mov_b32_dpp v41, v37 quad_perm:[2,3,0,1] row_mask:0xf bank_mask:0xf
	s_waitcnt lgkmcnt(0)
	v_add_f32_e32 v37, v37, v41
	s_nop 1
	v_mov_b32_dpp v41, v37 row_half_mirror row_mask:0xf bank_mask:0xf
	s_waitcnt lgkmcnt(0)
	v_add_f32_e32 v37, v37, v41
	s_nop 1
	v_mov_b32_dpp v41, v37 row_mirror row_mask:0xf bank_mask:0xf
	s_waitcnt lgkmcnt(0)
	v_add_f32_e32 v37, v37, v41
	global_load_dword v41, v[2:3], off offset:896
	v_mov_b32_e32 v47, v37
	s_nop 1
	v_permlane16_swap_b32_e32 v47, v37
	s_waitcnt lgkmcnt(0)
	v_add_f32_e32 v37, v37, v47
	v_fmamk_f32 v37, v37, 0x3b800000, v190
	v_mul_f32_e32 v47, 0x4f800000, v37
	v_cmp_gt_f32_e32 vcc, s56, v37
	s_nop 1
	v_cndmask_b32_e32 v37, v37, v47, vcc
	v_sqrt_f32_e32 v47, v37
	s_nop 0
	v_add_u32_e32 v48, -1, v47
	v_fma_f32 v49, -v48, v47, v37
	v_cmp_ge_f32_e64 s[0:1], 0, v49
	v_add_u32_e32 v49, 1, v47
	s_nop 0
	v_cndmask_b32_e64 v48, v47, v48, s[0:1]
	v_fma_f32 v47, -v49, v47, v37
	v_cmp_lt_f32_e64 s[0:1], 0, v47
	s_nop 1
	v_cndmask_b32_e64 v47, v48, v49, s[0:1]
	v_mul_f32_e32 v48, 0x37800000, v47
	v_cndmask_b32_e32 v47, v47, v48, vcc
	v_cmp_class_f32_e32 vcc, v37, v189
	s_nop 1
	v_cndmask_b32_e32 v37, v47, v37, vcc
	v_div_scale_f32 v47, s[0:1], v37, v37, s87
	v_rcp_f32_e32 v48, v47
	s_nop 0
	v_fma_f32 v49, -v47, v48, 1.0
	v_fmac_f32_e32 v48, v49, v48
	v_div_scale_f32 v49, vcc, s87, v37, s87
	v_mul_f32_e32 v50, v49, v48
	v_fma_f32 v51, -v47, v50, v49
	v_fmac_f32_e32 v50, v51, v48
	v_fma_f32 v47, -v47, v50, v49
	v_div_fmas_f32 v47, v47, v48, v50
	v_div_fixup_f32 v37, v47, v37, s87
	v_mul_f32_e32 v31, v31, v37
	s_waitcnt vmcnt(0)
	v_mul_f32_e32 v31, v38, v31
	v_bfe_u32 v38, v31, 16, 1
	v_add3_u32 v31, v31, v38, s88
	flat_store_short_d16_hi v[32:33], v31
	v_mul_f32_e32 v31, v40, v37
	v_mul_f32_e32 v31, v34, v31
	v_bfe_u32 v34, v31, 16, 1
	v_add3_u32 v31, v31, v34, s88
	flat_store_short_d16_hi v[32:33], v31 offset:64
	v_mul_f32_e32 v31, v42, v37
	v_mul_f32_e32 v31, v36, v31
	v_bfe_u32 v34, v31, 16, 1
	v_add3_u32 v31, v31, v34, s88
	flat_store_short_d16_hi v[32:33], v31 offset:128
	v_mul_f32_e32 v31, v43, v37
	v_mul_f32_e32 v31, v39, v31
	v_bfe_u32 v34, v31, 16, 1
	v_add3_u32 v31, v31, v34, s88
	flat_store_short_d16_hi v[32:33], v31 offset:192
	v_mul_f32_e32 v31, v35, v37
	v_mul_f32_e32 v31, v44, v31
	v_bfe_u32 v34, v31, 16, 1
	v_mul_f32_e32 v17, v17, v37
	v_add3_u32 v31, v31, v34, s88
	v_mul_f32_e32 v17, v17, v45
	flat_store_short_d16_hi v[32:33], v31 offset:256
	v_bfe_u32 v31, v17, 16, 1
	v_add3_u32 v17, v17, v31, s88
	flat_store_short_d16_hi v[32:33], v17 offset:320
	v_mul_f32_e32 v17, v30, v37
	v_mul_f32_e32 v17, v17, v46
	v_bfe_u32 v30, v17, 16, 1
	v_add3_u32 v17, v17, v30, s88
	flat_store_short_d16_hi v[32:33], v17 offset:384
	v_mul_f32_e32 v17, v29, v37
	v_mul_f32_e32 v17, v17, v41
	v_bfe_u32 v29, v17, 16, 1
	v_add3_u32 v17, v17, v29, s88
	flat_store_short_d16_hi v[32:33], v17 offset:448
	v_lshl_add_u64 v[30:31], v[32:33], 0, s[20:21]
	v_add_u32_e32 v17, 0x6400, v13
	ds_read2_b32 v[32:33], v17 offset1:32
	global_load_dword v36, v[2:3], off offset:512
	global_load_dword v37, v[2:3], off offset:640
	global_load_dword v38, v[2:3], off offset:768
	s_waitcnt lgkmcnt(0)
; #define LAS __attribute__((address_space(3)))
; __device__ __forceinline__ bf16_t f2bf(float f) { unsigned u = __float_as_uint(f); u += 0x7FFFu + ((u >> 16) & 1u); return (bf16_t)(u >> 16); }
; __device__ __forceinline__ void df_unit(LAS unsigned char* lds, const bf16_t* qkv, bf16_t* attout, const float* subg, int b_, int h_, int qb_, int wid, int) {
;     ...
;     if (jsel == 0) {
;         bf16_t* op = attout + (size_t)(b * SEQ + q0 + 4 * hi) * DM + 1024 + h * 256 + r32; const LAS float* xr = xb + (4 * hi) * 256 + r32;
; #pragma unroll
;         for (int r = 0; r < 16; ++r) { const int rowc = (r & 3) + 8 * (r >> 2); float ss = 0.f;
; #pragma unroll
;             for (int d = 0; d < 8; ++d) { o[d][r] -= xr[rowc * 256 + d * 32]; ss += o[d][r] * o[d][r]; }
;             ss += __shfl_xor(ss, 1); ss += __shfl_xor(ss, 2); ss += __shfl_xor(ss, 4); ss += __shfl_xor(ss, 8); ss += __shfl_xor(ss, 16);
;             const float rstd = (1.0f - LAMBDA_INIT) / sqrtf(ss * (1.0f / 256.0f) + SUBLN_EPS);
; #pragma unroll
;             for (int d = 0; d < 8; ++d) op[d * 32] = f2bf(o[d][r] * rstd * subg[d * 32 + r32]);
;             op += ((r & 3) == 3 ? 5 : 1) * DM; asm volatile("" : "+v"(op) :: "memory"); } }
	v_sub_f32_e32 v34, v28, v32
	ds_read2_b32 v[28:29], v17 offset0:64 offset1:96
	v_sub_f32_e32 v27, v27, v33
	ds_read2_b32 v[32:33], v17 offset0:128 offset1:160
	v_mul_f32_e32 v35, v27, v27
	v_fmac_f32_e32 v35, v34, v34
	s_waitcnt lgkmcnt(0)
	v_sub_f32_e32 v26, v26, v28
	v_sub_f32_e32 v28, v25, v29
	v_sub_f32_e32 v29, v24, v32
	ds_read2_b32 v[24:25], v17 offset0:192 offset1:224
	v_fmac_f32_e32 v35, v26, v26
	v_fmac_f32_e32 v35, v28, v28
	v_fmac_f32_e32 v35, v29, v29
	v_sub_f32_e32 v17, v23, v33
	v_fmac_f32_e32 v35, v17, v17
	s_waitcnt lgkmcnt(0)
	v_sub_f32_e32 v22, v22, v24
	v_fmac_f32_e32 v35, v22, v22
	v_sub_f32_e32 v21, v21, v25
	v_fmac_f32_e32 v35, v21, v21
	s_nop 1
	v_mov_b32_dpp v25, v35 quad_perm:[1,0,3,2] row_mask:0xf bank_mask:0xf
	global_load_dword v32, v[2:3], off
	global_load_dword v23, v[2:3], off offset:128
	global_load_dword v24, v[2:3], off offset:256
	global_load_dword v33, v[2:3], off offset:384
	s_waitcnt lgkmcnt(0)
	v_add_f32_e32 v25, v35, v25
	s_nop 1
	v_mov_b32_dpp v35, v25 quad_perm:[2,3,0,1] row_mask:0xf bank_mask:0xf
	s_waitcnt lgkmcnt(0)
	v_add_f32_e32 v25, v25, v35
	s_nop 1
	v_mov_b32_dpp v35, v25 row_half_mirror row_mask:0xf bank_mask:0xf
	s_waitcnt lgkmcnt(0)
	v_add_f32_e32 v25, v25, v35
	s_nop 1
	v_mov_b32_dpp v35, v25 row_mirror row_mask:0xf bank_mask:0xf
	s_waitcnt lgkmcnt(0)
	v_add_f32_e32 v25, v25, v35
	global_load_dword v35, v[2:3], off offset:896
	v_mov_b32_e32 v39, v25
	s_nop 1
	v_permlane16_swap_b32_e32 v39, v25
	s_waitcnt lgkmcnt(0)
	v_add_f32_e32 v25, v25, v39
	v_fmamk_f32 v25, v25, 0x3b800000, v190
	v_mul_f32_e32 v39, 0x4f800000, v25
	v_cmp_gt_f32_e32 vcc, s56, v25
	s_nop 1
	v_cndmask_b32_e32 v25, v25, v39, vcc
	v_sqrt_f32_e32 v39, v25
	s_nop 0
	v_add_u32_e32 v40, -1, v39
	v_fma_f32 v41, -v40, v39, v25
	v_cmp_ge_f32_e64 s[0:1], 0, v41
	v_add_u32_e32 v41, 1, v39
	s_nop 0
	v_cndmask_b32_e64 v40, v39, v40, s[0:1]
	v_fma_f32 v39, -v41, v39, v25
	v_cmp_lt_f32_e64 s[0:1], 0, v39
	s_nop 1
	v_cndmask_b32_e64 v39, v40, v41, s[0:1]
	v_mul_f32_e32 v40, 0x37800000, v39
	v_cndmask_b32_e32 v39, v39, v40, vcc
	v_cmp_class_f32_e32 vcc, v25, v189
	s_nop 1
	v_cndmask_b32_e32 v25, v39, v25, vcc
	v_div_scale_f32 v39, s[0:1], v25, v25, s87
	v_rcp_f32_e32 v40, v39
	s_nop 0
	v_fma_f32 v41, -v39, v40, 1.0
	v_fmac_f32_e32 v40, v41, v40
	v_div_scale_f32 v41, vcc, s87, v25, s87
	v_mul_f32_e32 v42, v41, v40
	v_fma_f32 v43, -v39, v42, v41
	v_fmac_f32_e32 v42, v43, v40
	v_fma_f32 v39, -v39, v42, v41
	v_div_fmas_f32 v39, v39, v40, v42
	v_div_fixup_f32 v25, v39, v25, s87
	v_mul_f32_e32 v27, v27, v25
	v_mul_f32_e32 v17, v17, v25
	s_waitcnt vmcnt(0)
	v_mul_f32_e32 v17, v17, v37
	v_mul_f32_e32 v34, v34, v25
	v_mul_f32_e32 v32, v32, v34
	v_mul_f32_e32 v23, v23, v27
	v_bfe_u32 v27, v23, 16, 1
	v_add3_u32 v23, v23, v27, s88
	flat_store_short_d16_hi v[30:31], v23 offset:64
	v_mul_f32_e32 v23, v26, v25
	v_mul_f32_e32 v23, v24, v23
	v_bfe_u32 v24, v23, 16, 1
	v_add3_u32 v23, v23, v24, s88
	flat_store_short_d16_hi v[30:31], v23 offset:128
	v_mul_f32_e32 v23, v28, v25
	v_mul_f32_e32 v23, v33, v23
	v_bfe_u32 v24, v23, 16, 1
	v_add3_u32 v23, v23, v24, s88
	flat_store_short_d16_hi v[30:31], v23 offset:192
	v_mul_f32_e32 v23, v29, v25
	v_mul_f32_e32 v23, v36, v23
	v_bfe_u32 v24, v23, 16, 1
	v_add3_u32 v23, v23, v24, s88
	flat_store_short_d16_hi v[30:31], v23 offset:256
	v_bfe_u32 v23, v17, 16, 1
	v_add3_u32 v17, v17, v23, s88
	flat_store_short_d16_hi v[30:31], v17 offset:320
	v_mul_f32_e32 v17, v22, v25
	v_mul_f32_e32 v17, v17, v38
	v_bfe_u32 v22, v17, 16, 1
	v_add3_u32 v17, v17, v22, s88
	flat_store_short_d16_hi v[30:31], v17 offset:384
	v_mul_f32_e32 v17, v21, v25
	v_mul_f32_e32 v17, v17, v35
	v_bfe_u32 v34, v32, 16, 1
	v_bfe_u32 v21, v17, 16, 1
	v_add3_u32 v32, v32, v34, s88
	v_add3_u32 v17, v17, v21, s88
	flat_store_short_d16_hi v[30:31], v32
	flat_store_short_d16_hi v[30:31], v17 offset:448
	v_lshl_add_u64 v[22:23], v[30:31], 0, s[20:21]
	v_add_u32_e32 v17, 0x6800, v13
	ds_read2_b32 v[24:25], v17 offset1:32
	global_load_dword v28, v[2:3], off offset:512
	global_load_dword v29, v[2:3], off offset:640
	global_load_dword v30, v[2:3], off offset:768
	s_waitcnt lgkmcnt(0)
	v_sub_f32_e32 v26, v20, v24
	ds_read2_b32 v[20:21], v17 offset0:64 offset1:96
	v_sub_f32_e32 v19, v19, v25
	ds_read2_b32 v[24:25], v17 offset0:128 offset1:160
	v_mul_f32_e32 v27, v19, v19
	v_fmac_f32_e32 v27, v26, v26
	s_waitcnt lgkmcnt(0)
	v_sub_f32_e32 v18, v18, v20
	v_sub_f32_e32 v20, v16, v21
	ds_read2_b32 v[16:17], v17 offset0:192 offset1:224
	v_fmac_f32_e32 v27, v18, v18
	v_fmac_f32_e32 v27, v20, v20
	v_sub_f32_e32 v15, v15, v24
	v_fmac_f32_e32 v27, v15, v15
	v_sub_f32_e32 v14, v14, v25
	v_fmac_f32_e32 v27, v14, v14
	s_waitcnt lgkmcnt(0)
	v_sub_f32_e32 v11, v11, v16
	v_fmac_f32_e32 v27, v11, v11
	v_sub_f32_e32 v12, v12, v17
	v_fmac_f32_e32 v27, v12, v12
	s_nop 1
	v_mov_b32_dpp v17, v27 quad_perm:[1,0,3,2] row_mask:0xf bank_mask:0xf
	global_load_dword v21, v[2:3], off
	global_load_dword v24, v[2:3], off offset:128
	global_load_dword v16, v[2:3], off offset:256
	global_load_dword v25, v[2:3], off offset:384
	s_waitcnt lgkmcnt(0)
	v_add_f32_e32 v17, v27, v17
	s_nop 1
	v_mov_b32_dpp v27, v17 quad_perm:[2,3,0,1] row_mask:0xf bank_mask:0xf
	s_waitcnt lgkmcnt(0)
	v_add_f32_e32 v17, v17, v27
	s_nop 1
	v_mov_b32_dpp v27, v17 row_half_mirror row_mask:0xf bank_mask:0xf
	s_waitcnt lgkmcnt(0)
	v_add_f32_e32 v17, v17, v27
	s_nop 1
	v_mov_b32_dpp v27, v17 row_mirror row_mask:0xf bank_mask:0xf
	s_waitcnt lgkmcnt(0)
	v_add_f32_e32 v17, v17, v27
	global_load_dword v27, v[2:3], off offset:896
	v_mov_b32_e32 v31, v17
	s_nop 1
	v_permlane16_swap_b32_e32 v31, v17
	s_waitcnt lgkmcnt(0)
; #define LAS __attribute__((address_space(3)))
; __device__ __forceinline__ bf16_t f2bf(float f) { unsigned u = __float_as_uint(f); u += 0x7FFFu + ((u >> 16) & 1u); return (bf16_t)(u >> 16); }
; __device__ __forceinline__ void df_unit(LAS unsigned char* lds, const bf16_t* qkv, bf16_t* attout, const float* subg, int b_, int h_, int qb_, int wid, int) {
;     ...
;     if (jsel == 0) {
;         bf16_t* op = attout + (size_t)(b * SEQ + q0 + 4 * hi) * DM + 1024 + h * 256 + r32; const LAS float* xr = xb + (4 * hi) * 256 + r32;
; #pragma unroll
;         for (int r = 0; r < 16; ++r) { const int rowc = (r & 3) + 8 * (r >> 2); float ss = 0.f;
; #pragma unroll
;             for (int d = 0; d < 8; ++d) { o[d][r] -= xr[rowc * 256 + d * 32]; ss += o[d][r] * o[d][r]; }
;             ss += __shfl_xor(ss, 1); ss += __shfl_xor(ss, 2); ss += __shfl_xor(ss, 4); ss += __shfl_xor(ss, 8); ss += __shfl_xor(ss, 16);
;             const float rstd = (1.0f - LAMBDA_INIT) / sqrtf(ss * (1.0f / 256.0f) + SUBLN_EPS);
; #pragma unroll
;             for (int d = 0; d < 8; ++d) op[d * 32] = f2bf(o[d][r] * rstd * subg[d * 32 + r32]);
;             op += ((r & 3) == 3 ? 5 : 1) * DM; asm volatile("" : "+v"(op) :: "memory"); } }
	v_add_f32_e32 v17, v17, v31
	v_fmamk_f32 v17, v17, 0x3b800000, v190
	v_mul_f32_e32 v31, 0x4f800000, v17
	v_cmp_gt_f32_e32 vcc, s56, v17
	s_nop 1
	v_cndmask_b32_e32 v17, v17, v31, vcc
	v_sqrt_f32_e32 v31, v17
	s_nop 0
	v_add_u32_e32 v32, -1, v31
	v_fma_f32 v33, -v32, v31, v17
	v_cmp_ge_f32_e64 s[0:1], 0, v33
	v_add_u32_e32 v33, 1, v31
	s_nop 0
	v_cndmask_b32_e64 v32, v31, v32, s[0:1]
	v_fma_f32 v31, -v33, v31, v17
	v_cmp_lt_f32_e64 s[0:1], 0, v31
	s_nop 1
	v_cndmask_b32_e64 v31, v32, v33, s[0:1]
	v_mul_f32_e32 v32, 0x37800000, v31
	v_cndmask_b32_e32 v31, v31, v32, vcc
	v_cmp_class_f32_e32 vcc, v17, v189
	s_nop 1
	v_cndmask_b32_e32 v17, v31, v17, vcc
	v_div_scale_f32 v31, s[0:1], v17, v17, s87
	v_rcp_f32_e32 v32, v31
	s_nop 0
	v_fma_f32 v33, -v31, v32, 1.0
	v_fmac_f32_e32 v32, v33, v32
	v_div_scale_f32 v33, vcc, s87, v17, s87
	v_mul_f32_e32 v34, v33, v32
	v_fma_f32 v35, -v31, v34, v33
	v_fmac_f32_e32 v34, v35, v32
	v_fma_f32 v31, -v31, v34, v33
	v_div_fmas_f32 v31, v31, v32, v34
	v_div_fixup_f32 v17, v31, v17, s87
	v_mul_f32_e32 v18, v18, v17
	v_mul_f32_e32 v15, v15, v17
	s_waitcnt vmcnt(0)
	v_mul_f32_e32 v15, v28, v15
	v_mul_f32_e32 v14, v14, v17
	v_mul_f32_e32 v14, v14, v29
	v_mul_f32_e32 v11, v11, v17
	v_mul_f32_e32 v11, v11, v30
	v_mul_f32_e32 v26, v26, v17
	v_mul_f32_e32 v21, v21, v26
	v_mul_f32_e32 v16, v16, v18
	v_bfe_u32 v18, v16, 16, 1
	v_add3_u32 v16, v16, v18, s88
	flat_store_short_d16_hi v[22:23], v16 offset:128
	v_mul_f32_e32 v16, v20, v17
	v_mul_f32_e32 v16, v25, v16
	v_bfe_u32 v18, v16, 16, 1
	v_add3_u32 v16, v16, v18, s88
	flat_store_short_d16_hi v[22:23], v16 offset:192
	v_bfe_u32 v16, v15, 16, 1
	v_add3_u32 v15, v15, v16, s88
	flat_store_short_d16_hi v[22:23], v15 offset:256
	v_bfe_u32 v15, v14, 16, 1
	v_add3_u32 v14, v14, v15, s88
	flat_store_short_d16_hi v[22:23], v14 offset:320
	v_bfe_u32 v14, v11, 16, 1
	v_add3_u32 v11, v11, v14, s88
	v_bfe_u32 v26, v21, 16, 1
	v_mul_f32_e32 v19, v19, v17
	flat_store_short_d16_hi v[22:23], v11 offset:384
	v_mul_f32_e32 v11, v12, v17
	v_add3_u32 v21, v21, v26, s88
	v_mul_f32_e32 v19, v24, v19
	v_mul_f32_e32 v11, v11, v27
	flat_store_short_d16_hi v[22:23], v21
	v_bfe_u32 v21, v19, 16, 1
	v_bfe_u32 v12, v11, 16, 1
	v_add3_u32 v19, v19, v21, s88
	v_add3_u32 v11, v11, v12, s88
	flat_store_short_d16_hi v[22:23], v19 offset:64
	flat_store_short_d16_hi v[22:23], v11 offset:448
	v_lshl_add_u64 v[14:15], v[22:23], 0, s[20:21]
	v_add_u32_e32 v16, 0x6c00, v13
	ds_read2_b32 v[12:13], v16 offset1:32
	global_load_dword v19, v[2:3], off offset:512
	global_load_dword v20, v[2:3], off offset:640
	global_load_dword v21, v[2:3], off offset:768
	s_waitcnt lgkmcnt(0)
	v_sub_f32_e32 v17, v10, v12
	ds_read2_b32 v[10:11], v16 offset0:64 offset1:96
	v_sub_f32_e32 v9, v9, v13
	ds_read2_b32 v[12:13], v16 offset0:128 offset1:160
	v_mul_f32_e32 v18, v9, v9
	v_fmac_f32_e32 v18, v17, v17
	s_waitcnt lgkmcnt(0)
	v_sub_f32_e32 v8, v8, v10
	v_sub_f32_e32 v10, v7, v11
	v_sub_f32_e32 v11, v6, v12
	global_load_dword v12, v[2:3], off
	ds_read2_b32 v[6:7], v16 offset0:192 offset1:224
	v_sub_f32_e32 v5, v5, v13
	global_load_dword v13, v[2:3], off offset:128
	global_load_dword v16, v[2:3], off offset:384
	v_fmac_f32_e32 v18, v8, v8
	s_waitcnt lgkmcnt(0)
	v_sub_f32_e32 v4, v4, v6
	global_load_dword v6, v[2:3], off offset:256
	v_fmac_f32_e32 v18, v10, v10
	v_fmac_f32_e32 v18, v11, v11
	v_fmac_f32_e32 v18, v5, v5
	v_fmac_f32_e32 v18, v4, v4
	v_sub_f32_e32 v0, v0, v7
	v_fmac_f32_e32 v18, v0, v0
	s_nop 1
	v_mov_b32_dpp v7, v18 quad_perm:[1,0,3,2] row_mask:0xf bank_mask:0xf
	global_load_dword v2, v[2:3], off offset:896
	s_waitcnt lgkmcnt(0)
	v_add_f32_e32 v7, v18, v7
	s_nop 1
	v_mov_b32_dpp v18, v7 quad_perm:[2,3,0,1] row_mask:0xf bank_mask:0xf
	s_waitcnt lgkmcnt(0)
	v_add_f32_e32 v7, v7, v18
	s_nop 1
	v_mov_b32_dpp v18, v7 row_half_mirror row_mask:0xf bank_mask:0xf
	s_waitcnt lgkmcnt(0)
	v_add_f32_e32 v7, v7, v18
	s_nop 1
	v_mov_b32_dpp v18, v7 row_mirror row_mask:0xf bank_mask:0xf
	s_waitcnt lgkmcnt(0)
	v_add_f32_e32 v7, v7, v18
	v_mov_b32_e32 v3, v7
	s_nop 1
	v_permlane16_swap_b32_e32 v3, v7
	s_waitcnt lgkmcnt(0)
	v_add_f32_e32 v3, v7, v3
	v_fmamk_f32 v3, v3, 0x3b800000, v190
	v_mul_f32_e32 v7, 0x4f800000, v3
	v_cmp_gt_f32_e32 vcc, s56, v3
	s_nop 1
	v_cndmask_b32_e32 v3, v3, v7, vcc
	v_sqrt_f32_e32 v7, v3
	s_nop 0
	v_add_u32_e32 v18, -1, v7
	v_fma_f32 v22, -v18, v7, v3
	v_cmp_ge_f32_e64 s[0:1], 0, v22
	v_add_u32_e32 v22, 1, v7
	s_nop 0
	v_cndmask_b32_e64 v18, v7, v18, s[0:1]
	v_fma_f32 v7, -v22, v7, v3
	v_cmp_lt_f32_e64 s[0:1], 0, v7
	s_nop 1
	v_cndmask_b32_e64 v7, v18, v22, s[0:1]
	v_mul_f32_e32 v18, 0x37800000, v7
	v_cndmask_b32_e32 v7, v7, v18, vcc
	v_cmp_class_f32_e32 vcc, v3, v189
	s_nop 1
	v_cndmask_b32_e32 v3, v7, v3, vcc
	v_div_scale_f32 v7, s[0:1], v3, v3, s87
	v_rcp_f32_e32 v18, v7
	s_nop 0
	v_fma_f32 v22, -v7, v18, 1.0
	v_fmac_f32_e32 v18, v22, v18
	v_div_scale_f32 v22, vcc, s87, v3, s87
	v_mul_f32_e32 v23, v22, v18
	v_fma_f32 v24, -v7, v23, v22
	v_fmac_f32_e32 v23, v24, v18
	v_fma_f32 v7, -v7, v23, v22
	v_div_fmas_f32 v7, v7, v18, v23
	v_div_fixup_f32 v3, v7, v3, s87
	v_mul_f32_e32 v7, v17, v3
	s_waitcnt vmcnt(0)
	v_mul_f32_e32 v7, v12, v7
	v_bfe_u32 v12, v7, 16, 1
	v_add3_u32 v7, v7, v12, s88
	flat_store_short_d16_hi v[14:15], v7
	v_mul_f32_e32 v7, v9, v3
	v_mul_f32_e32 v7, v13, v7
	v_bfe_u32 v9, v7, 16, 1
	v_add3_u32 v7, v7, v9, s88
	flat_store_short_d16_hi v[14:15], v7 offset:64
	v_mul_f32_e32 v7, v8, v3
	v_mul_f32_e32 v6, v6, v7
	v_bfe_u32 v7, v6, 16, 1
	v_add3_u32 v6, v6, v7, s88
	flat_store_short_d16_hi v[14:15], v6 offset:128
	v_mul_f32_e32 v6, v10, v3
	v_mul_f32_e32 v6, v16, v6
	v_bfe_u32 v7, v6, 16, 1
	v_add3_u32 v6, v6, v7, s88
	flat_store_short_d16_hi v[14:15], v6 offset:192
	v_mul_f32_e32 v6, v11, v3
	v_mul_f32_e32 v6, v19, v6
	v_bfe_u32 v7, v6, 16, 1
	v_mul_f32_e32 v5, v5, v3
	v_add3_u32 v6, v6, v7, s88
	v_mul_f32_e32 v5, v5, v20
	flat_store_short_d16_hi v[14:15], v6 offset:256
	v_bfe_u32 v6, v5, 16, 1
	v_mul_f32_e32 v4, v4, v3
	v_mul_f32_e32 v0, v0, v3
	v_add3_u32 v5, v5, v6, s88
	v_mul_f32_e32 v4, v4, v21
	v_mul_f32_e32 v0, v0, v2
	flat_store_short_d16_hi v[14:15], v5 offset:320
	v_bfe_u32 v5, v4, 16, 1
	v_bfe_u32 v2, v0, 16, 1
	v_add3_u32 v4, v4, v5, s88
	v_add3_u32 v0, v0, v2, s88
	flat_store_short_d16_hi v[14:15], v4 offset:384
	flat_store_short_d16_hi v[14:15], v0 offset:448
	v_lshl_add_u64 v[2:3], v[14:15], 0, s[22:23]
	s_branch .LBB0_260
